# barrier: poll arrival counter + early L1 inv; spatial: hoisted bias loads and W_s staging loads; no cg entry sync
# speedup vs baseline: 1.0085x; 1.0085x over previous
; #define KWS(F_) (*(unsigned char* const __attribute__((address_space(4)))*)((F_).kp + 136))
; #define ws KWS(F)
; __device__ __forceinline__ void p0_prologue(const Frame& F, unsigned char* ws) {
;     const int gw = F.vcu * NWAVES + F.wave, NGW = F.G * NWAVES;
;     constexpr int I_WIN = (D / 64) * (4096 / 32), I_WOG = (GE / 64) * (D / 32), I_WOF = (D / 64) * (D / 32), I_W2 = (FF / 64) * (D / 32);
;     constexpr int NITEMS = 2 * (I_WIN + I_WOG + I_WIN + I_WOF) + 4 * (I_WIN + I_W2);
;     for (int it = gw; it < NITEMS; it += 4 * NGW) {
;         const bool h1 = it + NGW < NITEMS, h2 = it + 2 * NGW < NITEMS, h3 = it + 3 * NGW < NITEMS;
;         const P0Item a = p0_decode(F, ws, it), b = p0_decode(F, ws, h1 ? it + NGW : it), c = p0_decode(F, ws, h2 ? it + 2 * NGW : it), d = p0_decode(F, ws, h3 ? it + 3 * NGW : it);
; __global__ void __launch_bounds__(NWAVES * 64, 2) mk_fwd(Args args) {
;     ...
;     if (args.ph_hi - args.ph_lo > 1) bar = xcd_barrier_post((unsigned*)(KWS(F) + WS_CTL) + CW_BAR, bst);
;     const int lo = args.ph_lo, hi = args.ph_hi; int ph = 0;
;     if (hi - lo > 1) cg::this_grid().sync();
.LBB0_9:
	s_or_b64 exec, exec, s[0:1]
	v_lshrrev_b32_e32 v1, 20, v0
	v_lshrrev_b32_e32 v0, 10, v0
	v_or_b32_e32 v0, v0, v1
	s_movk_i32 s0, 0x3ff
	v_and_or_b32 v0, v0, s0, v161
	v_cmp_eq_u32_e32 vcc, 0, v0
	s_waitcnt lgkmcnt(0)
	s_barrier
.LBB0_20:
	s_lshr_b32 s71, s33, 6
	s_cmp_lt_i32 s92, 1
	s_cselect_b64 s[0:1], -1, 0
	s_cmp_gt_i32 s93, 0
	s_cselect_b64 s[4:5], -1, 0
	s_and_b64 s[0:1], s[0:1], s[4:5]
	s_andn2_b64 vcc, exec, s[0:1]
	s_cbranch_vccnz .LBB0_182
	s_mov_b32 s0, -1
	s_lshl_b32 s4, s96, 3
	v_mbcnt_lo_u32_b32 v0, s0, 0
	v_mbcnt_hi_u32_b32 v163, s0, v0
	s_load_dwordx2 s[0:1], s[94:95], 0x88
	s_add_i32 s6, s4, s71
	s_lshl_b32 s72, s3, 3
	s_lshl_b32 s8, s3, 4
	s_mov_b32 s5, 0
	s_cmpk_gt_i32 s6, 0x6bff
	v_lshlrev_b32_e32 v0, 3, v163
	s_cbranch_scc1 .LBB0_116
	s_waitcnt lgkmcnt(0)
	s_add_u32 s7, s0, 0x5400000
	s_addc_u32 s9, s1, 0
	s_add_u32 s73, s0, 0x3400000
	s_addc_u32 s74, s1, 0
	s_add_u32 s75, s0, 0x3000000
	s_addc_u32 s76, s1, 0
	s_add_u32 s77, s0, 0x2000000
	s_addc_u32 s78, s1, 0
	s_add_u32 s79, s0, 0x1800000
	s_addc_u32 s80, s1, 0
	v_lshrrev_b32_e32 v1, 1, v163
	s_add_u32 s81, s0, 0x800000
	v_and_b32_e32 v162, 60, v1
	v_mov_b32_e32 v165, 0
	s_addc_u32 s82, s1, 0
	s_lshl_b32 s83, s3, 5
	v_and_b32_e32 v160, 56, v0
	s_add_i32 s84, s6, 0xffffd400
	s_mul_i32 s85, s3, 24
	v_lshlrev_b32_e32 v166, 2, v162
	v_mov_b32_e32 v167, v165
	s_movk_i32 s86, 0x7fff
	s_mov_b32 s87, 0xffff0000
	s_mov_b32 s88, s6
	s_branch .LBB0_25

; __device__ __forceinline__ unsigned xb_ld(unsigned* p)              { return __hip_atomic_load(p, __ATOMIC_RELAXED, __HIP_MEMORY_SCOPE_AGENT); }
; __device__ __forceinline__ unsigned xb_add(unsigned* p, unsigned v) { return __hip_atomic_fetch_add(p, v, __ATOMIC_RELAXED, __HIP_MEMORY_SCOPE_AGENT); }
; #define XB_SPIN(cond, bar) do { unsigned _sp = 0; while (cond) { __builtin_amdgcn_s_sleep(1); \
;     if ((++_sp & 255u) == 0u) { if (xb_ld(&(bar)[XB_TMO])) break; if (_sp > XB_SPIN_CAP) { atomicAdd(&(bar)[XB_TMO], 1u); break; } } } } while (0)
; __device__ __forceinline__ void xcd_barrier(const XcdBarrier& b, const bool local_only = false) {
;     ...
;         const unsigned old = xb_add(&bar[XB_XSUB(b.x)], 1u);
;         const unsigned gen = old / nloc;
;         if (old + 1u == (gen + 1u) * nloc) {
;             if (!local_only) {
;             __builtin_amdgcn_fence(__ATOMIC_RELEASE, "agent");
;             asm volatile("s_waitcnt vmcnt(0)" ::: "memory");
;             const unsigned og = xb_add(&bar[XB_TOP], 1u);
;             const unsigned tg = og / nx;
;             if (og + 1u == (tg + 1u) * nx) xb_add(&bar[XB_TOPGEN], 1u);
;             else XB_SPIN(xb_ld(&bar[XB_TOPGEN]) == tg, bar);
;             }
;             __builtin_amdgcn_fence(__ATOMIC_ACQUIRE, "agent");
;             xb_add(&bar[XB_XGEN(b.x)], 1u);
;             asm volatile("s_waitcnt vmcnt(0)" ::: "memory");
;         } else {
;             XB_SPIN(xb_ld(&bar[XB_XGEN(b.x)]) == gen, bar);
;             __builtin_amdgcn_fence(__ATOMIC_ACQUIRE, "agent");
;             asm volatile("s_waitcnt vmcnt(0)" ::: "memory");
.LBB0_289:
	s_or_b64 exec, exec, s[14:15]
	buffer_inv sc1
	v_cvt_f32_u32_e32 v3, v0
	s_waitcnt vmcnt(0)
	v_readfirstlane_b32 s6, v2
	v_sub_u32_e32 v2, 0, v0
	v_rcp_iflag_f32_e32 v3, v3
	v_add_u32_e32 v4, s6, v1
	v_mul_f32_e32 v3, 0x4f7ffffe, v3
	v_cvt_u32_f32_e32 v3, v3
	v_mul_lo_u32 v1, v2, v3
	v_mul_hi_u32 v1, v3, v1
	v_add_u32_e32 v1, v3, v1
	v_mul_hi_u32 v1, v4, v1
	v_mul_lo_u32 v2, v1, v0
	v_sub_u32_e32 v2, v4, v2
	v_add_u32_e32 v3, 1, v1
	v_cmp_ge_u32_e32 vcc, v2, v0
	s_nop 1
	v_cndmask_b32_e32 v1, v1, v3, vcc
	v_sub_u32_e32 v3, v2, v0
	v_cndmask_b32_e32 v2, v2, v3, vcc
	v_add_u32_e32 v3, 1, v1
	v_cmp_ge_u32_e32 vcc, v2, v0
	v_add_u32_e32 v2, 1, v4
	s_nop 0
	v_cndmask_b32_e32 v1, v1, v3, vcc
	v_mul_lo_u32 v3, v0, v1
	v_add_u32_e32 v0, v3, v0
	v_cmp_ne_u32_e32 vcc, v2, v0
	s_and_saveexec_b64 s[6:7], vcc
	s_xor_b64 s[6:7], exec, s[6:7]
	s_cbranch_execz .LBB0_303
	v_readlane_b32 vcc_lo, v253, 2
	v_readlane_b32 vcc_hi, v253, 3
	s_nop 0
	s_and_b64 vcc, exec, vcc
	s_cbranch_vccnz .Lxb_gen_1
	v_mov_b32_e32 v4, v0
	v_mov_b32_e32 v5, 0x1000
	s_mov_b32 s20, 0
.Lxb_poll_1:
	global_load_dword v0, v5, s[4:5] offset:1024 sc1
	s_waitcnt vmcnt(0)
	v_cmp_ge_u32_e32 vcc, v0, v4
	s_cbranch_vccnz .Lxb_arr_1
	s_sleep 1
	s_add_u32 s20, s20, 1
	s_cmp_lt_u32 s20, 0x100000
	s_cbranch_scc1 .Lxb_poll_1
	s_branch .Lxb_arr_1
.Lxb_gen_1:
	v_mov_b32_e32 v0, 0x2000
	global_load_dword v0, v0, s[4:5] offset:1024 sc1
	s_add_u32 s20, s4, 0x2400
	s_addc_u32 s21, s5, 0
	s_waitcnt vmcnt(0)
	v_cmp_eq_u32_e32 vcc, v0, v1
	s_and_saveexec_b64 s[18:19], vcc
	s_cbranch_execz .LBB0_302
	s_add_u32 s14, s24, 0x1200
	s_addc_u32 s15, s25, 0
	s_mov_b32 s42, 1
	s_mov_b64 s[22:23], 0
	s_branch .LBB0_293

; __device__ __forceinline__ unsigned xb_ld(unsigned* p)              { return __hip_atomic_load(p, __ATOMIC_RELAXED, __HIP_MEMORY_SCOPE_AGENT); }
; #define XB_SPIN(cond, bar) do { unsigned _sp = 0; while (cond) { __builtin_amdgcn_s_sleep(1); \
;     if ((++_sp & 255u) == 0u) { if (xb_ld(&(bar)[XB_TMO])) break; if (_sp > XB_SPIN_CAP) { atomicAdd(&(bar)[XB_TMO], 1u); break; } } } } while (0)
; __device__ __forceinline__ void xcd_barrier(const XcdBarrier& b, const bool local_only = false) {
;     ...
;         } else {
;             XB_SPIN(xb_ld(&bar[XB_XGEN(b.x)]) == gen, bar);
;             __builtin_amdgcn_fence(__ATOMIC_ACQUIRE, "agent");
;             asm volatile("s_waitcnt vmcnt(0)" ::: "memory");
;         }
.LBB0_302:
	s_or_b64 exec, exec, s[18:19]
.Lxb_arr_1:
	s_waitcnt vmcnt(0) lgkmcnt(0)
	v_readlane_b32 vcc_lo, v253, 2
	v_readlane_b32 vcc_hi, v253, 3
	s_nop 0
	s_and_b64 vcc, exec, vcc
	s_cbranch_vccz .Lxb_nl_skip_1
	buffer_inv sc1
.Lxb_nl_skip_1:
	s_waitcnt vmcnt(0)

; __device__ __forceinline__ unsigned xb_ld(unsigned* p)              { return __hip_atomic_load(p, __ATOMIC_RELAXED, __HIP_MEMORY_SCOPE_AGENT); }
; __device__ __forceinline__ unsigned xb_add(unsigned* p, unsigned v) { return __hip_atomic_fetch_add(p, v, __ATOMIC_RELAXED, __HIP_MEMORY_SCOPE_AGENT); }
; #define XB_SPIN(cond, bar) do { unsigned _sp = 0; while (cond) { __builtin_amdgcn_s_sleep(1); \
;     if ((++_sp & 255u) == 0u) { if (xb_ld(&(bar)[XB_TMO])) break; if (_sp > XB_SPIN_CAP) { atomicAdd(&(bar)[XB_TMO], 1u); break; } } } } while (0)
; __device__ __forceinline__ void xcd_barrier(const XcdBarrier& b, const bool local_only = false) {
;     ...
;         const unsigned old = xb_add(&bar[XB_XSUB(b.x)], 1u);
;         const unsigned gen = old / nloc;
;         if (old + 1u == (gen + 1u) * nloc) {
;             if (!local_only) {
;             __builtin_amdgcn_fence(__ATOMIC_RELEASE, "agent");
;             asm volatile("s_waitcnt vmcnt(0)" ::: "memory");
;             const unsigned og = xb_add(&bar[XB_TOP], 1u);
;             const unsigned tg = og / nx;
;             if (og + 1u == (tg + 1u) * nx) xb_add(&bar[XB_TOPGEN], 1u);
;             else XB_SPIN(xb_ld(&bar[XB_TOPGEN]) == tg, bar);
;             }
;             __builtin_amdgcn_fence(__ATOMIC_ACQUIRE, "agent");
;             xb_add(&bar[XB_XGEN(b.x)], 1u);
;             asm volatile("s_waitcnt vmcnt(0)" ::: "memory");
;         } else {
;             XB_SPIN(xb_ld(&bar[XB_XGEN(b.x)]) == gen, bar);
;             __builtin_amdgcn_fence(__ATOMIC_ACQUIRE, "agent");
;             asm volatile("s_waitcnt vmcnt(0)" ::: "memory");
.LBB0_456:
	s_or_b64 exec, exec, s[8:9]
	buffer_inv sc1
	v_cvt_f32_u32_e32 v3, v0
	s_waitcnt vmcnt(0)
	v_readfirstlane_b32 s6, v2
	v_sub_u32_e32 v2, 0, v0
	v_rcp_iflag_f32_e32 v3, v3
	v_add_u32_e32 v4, s6, v1
	v_mul_f32_e32 v3, 0x4f7ffffe, v3
	v_cvt_u32_f32_e32 v3, v3
	v_mul_lo_u32 v1, v2, v3
	v_mul_hi_u32 v1, v3, v1
	v_add_u32_e32 v1, v3, v1
	v_mul_hi_u32 v1, v4, v1
	v_mul_lo_u32 v2, v1, v0
	v_sub_u32_e32 v2, v4, v2
	v_add_u32_e32 v3, 1, v1
	v_cmp_ge_u32_e32 vcc, v2, v0
	s_nop 1
	v_cndmask_b32_e32 v1, v1, v3, vcc
	v_sub_u32_e32 v3, v2, v0
	v_cndmask_b32_e32 v2, v2, v3, vcc
	v_add_u32_e32 v3, 1, v1
	v_cmp_ge_u32_e32 vcc, v2, v0
	v_add_u32_e32 v2, 1, v4
	s_nop 0
	v_cndmask_b32_e32 v1, v1, v3, vcc
	v_mul_lo_u32 v3, v0, v1
	v_add_u32_e32 v0, v3, v0
	v_cmp_ne_u32_e32 vcc, v2, v0
	s_and_saveexec_b64 s[6:7], vcc
	s_xor_b64 s[6:7], exec, s[6:7]
	s_cbranch_execz .LBB0_470
	v_readlane_b32 vcc_lo, v253, 2
	v_readlane_b32 vcc_hi, v253, 3
	s_nop 0
	s_and_b64 vcc, exec, vcc
	s_cbranch_vccnz .Lxb_gen_2
	v_mov_b32_e32 v4, v0
	v_mov_b32_e32 v5, 0x1000
	s_mov_b32 s18, 0
.Lxb_poll_2:
	global_load_dword v0, v5, s[4:5] offset:1024 sc1
	s_waitcnt vmcnt(0)
	v_cmp_ge_u32_e32 vcc, v0, v4
	s_cbranch_vccnz .Lxb_arr_2
	s_sleep 1
	s_add_u32 s18, s18, 1
	s_cmp_lt_u32 s18, 0x100000
	s_cbranch_scc1 .Lxb_poll_2
	s_branch .Lxb_arr_2
.Lxb_gen_2:
	v_mov_b32_e32 v0, 0x2000
	global_load_dword v0, v0, s[4:5] offset:1024 sc1
	s_add_u32 s18, s4, 0x2400
	s_addc_u32 s19, s5, 0
	s_waitcnt vmcnt(0)
	v_cmp_eq_u32_e32 vcc, v0, v1
	s_and_saveexec_b64 s[8:9], vcc
	s_cbranch_execz .LBB0_469
	s_add_u32 s14, s24, 0x1200
	s_addc_u32 s15, s25, 0
	s_mov_b32 s40, 1
	s_mov_b64 s[20:21], 0
	s_branch .LBB0_460

; __device__ __forceinline__ unsigned xb_ld(unsigned* p)              { return __hip_atomic_load(p, __ATOMIC_RELAXED, __HIP_MEMORY_SCOPE_AGENT); }
; #define XB_SPIN(cond, bar) do { unsigned _sp = 0; while (cond) { __builtin_amdgcn_s_sleep(1); \
;     if ((++_sp & 255u) == 0u) { if (xb_ld(&(bar)[XB_TMO])) break; if (_sp > XB_SPIN_CAP) { atomicAdd(&(bar)[XB_TMO], 1u); break; } } } } while (0)
; __device__ __forceinline__ void xcd_barrier(const XcdBarrier& b, const bool local_only = false) {
;     ...
;         } else {
;             XB_SPIN(xb_ld(&bar[XB_XGEN(b.x)]) == gen, bar);
;             __builtin_amdgcn_fence(__ATOMIC_ACQUIRE, "agent");
;             asm volatile("s_waitcnt vmcnt(0)" ::: "memory");
;         }
.LBB0_469:
	s_or_b64 exec, exec, s[8:9]
.Lxb_arr_2:
	s_waitcnt vmcnt(0) lgkmcnt(0)
	v_readlane_b32 vcc_lo, v253, 2
	v_readlane_b32 vcc_hi, v253, 3
	s_nop 0
	s_and_b64 vcc, exec, vcc
	s_cbranch_vccz .Lxb_nl_skip_3
	buffer_inv sc1
.Lxb_nl_skip_3:
	s_waitcnt vmcnt(0)

; __device__ __forceinline__ unsigned xb_ld(unsigned* p)              { return __hip_atomic_load(p, __ATOMIC_RELAXED, __HIP_MEMORY_SCOPE_AGENT); }
; __device__ __forceinline__ unsigned xb_add(unsigned* p, unsigned v) { return __hip_atomic_fetch_add(p, v, __ATOMIC_RELAXED, __HIP_MEMORY_SCOPE_AGENT); }
; #define XB_SPIN(cond, bar) do { unsigned _sp = 0; while (cond) { __builtin_amdgcn_s_sleep(1); \
;     if ((++_sp & 255u) == 0u) { if (xb_ld(&(bar)[XB_TMO])) break; if (_sp > XB_SPIN_CAP) { atomicAdd(&(bar)[XB_TMO], 1u); break; } } } } while (0)
; __device__ __forceinline__ void xcd_barrier(const XcdBarrier& b, const bool local_only = false) {
;     ...
;         const unsigned old = xb_add(&bar[XB_XSUB(b.x)], 1u);
;         const unsigned gen = old / nloc;
;         if (old + 1u == (gen + 1u) * nloc) {
;             if (!local_only) {
;             __builtin_amdgcn_fence(__ATOMIC_RELEASE, "agent");
;             asm volatile("s_waitcnt vmcnt(0)" ::: "memory");
;             const unsigned og = xb_add(&bar[XB_TOP], 1u);
;             const unsigned tg = og / nx;
;             if (og + 1u == (tg + 1u) * nx) xb_add(&bar[XB_TOPGEN], 1u);
;             else XB_SPIN(xb_ld(&bar[XB_TOPGEN]) == tg, bar);
;             }
;             __builtin_amdgcn_fence(__ATOMIC_ACQUIRE, "agent");
;             xb_add(&bar[XB_XGEN(b.x)], 1u);
;             asm volatile("s_waitcnt vmcnt(0)" ::: "memory");
;         } else {
;             XB_SPIN(xb_ld(&bar[XB_XGEN(b.x)]) == gen, bar);
;             __builtin_amdgcn_fence(__ATOMIC_ACQUIRE, "agent");
;             asm volatile("s_waitcnt vmcnt(0)" ::: "memory");
.LBB0_553:
	s_or_b64 exec, exec, s[14:15]
	buffer_inv sc1
	v_cvt_f32_u32_e32 v3, v0
	s_waitcnt vmcnt(0)
	v_readfirstlane_b32 s6, v2
	v_sub_u32_e32 v2, 0, v0
	v_rcp_iflag_f32_e32 v3, v3
	v_add_u32_e32 v4, s6, v1
	v_mul_f32_e32 v3, 0x4f7ffffe, v3
	v_cvt_u32_f32_e32 v3, v3
	v_mul_lo_u32 v1, v2, v3
	v_mul_hi_u32 v1, v3, v1
	v_add_u32_e32 v1, v3, v1
	v_mul_hi_u32 v1, v4, v1
	v_mul_lo_u32 v2, v1, v0
	v_sub_u32_e32 v2, v4, v2
	v_add_u32_e32 v3, 1, v1
	v_cmp_ge_u32_e32 vcc, v2, v0
	s_nop 1
	v_cndmask_b32_e32 v1, v1, v3, vcc
	v_sub_u32_e32 v3, v2, v0
	v_cndmask_b32_e32 v2, v2, v3, vcc
	v_add_u32_e32 v3, 1, v1
	v_cmp_ge_u32_e32 vcc, v2, v0
	v_add_u32_e32 v2, 1, v4
	s_nop 0
	v_cndmask_b32_e32 v1, v1, v3, vcc
	v_mul_lo_u32 v3, v0, v1
	v_add_u32_e32 v0, v3, v0
	v_cmp_ne_u32_e32 vcc, v2, v0
	s_and_saveexec_b64 s[6:7], vcc
	s_xor_b64 s[6:7], exec, s[6:7]
	s_cbranch_execz .LBB0_567
	v_readlane_b32 vcc_lo, v253, 2
	v_readlane_b32 vcc_hi, v253, 3
	s_nop 0
	s_and_b64 vcc, exec, vcc
	s_cbranch_vccnz .Lxb_gen_3
	v_mov_b32_e32 v4, v0
	v_mov_b32_e32 v5, 0x1000
	s_mov_b32 s22, 0
.Lxb_poll_3:
	global_load_dword v0, v5, s[4:5] offset:1024 sc1
	s_waitcnt vmcnt(0)
	v_cmp_ge_u32_e32 vcc, v0, v4
	s_cbranch_vccnz .Lxb_arr_3
	s_sleep 1
	s_add_u32 s22, s22, 1
	s_cmp_lt_u32 s22, 0x100000
	s_cbranch_scc1 .Lxb_poll_3
	s_branch .Lxb_arr_3
.Lxb_gen_3:
	v_mov_b32_e32 v0, 0x2000
	global_load_dword v0, v0, s[4:5] offset:1024 sc1
	s_add_u32 s22, s4, 0x2400
	s_addc_u32 s23, s5, 0
	s_waitcnt vmcnt(0)
	v_cmp_eq_u32_e32 vcc, v0, v1
	s_and_saveexec_b64 s[20:21], vcc
	s_cbranch_execz .LBB0_566
	s_add_u32 s14, s18, 0x1200
	s_addc_u32 s15, s19, 0
	s_mov_b32 s42, 1
	s_mov_b64 s[24:25], 0
	s_branch .LBB0_557

; __device__ __forceinline__ unsigned xb_ld(unsigned* p)              { return __hip_atomic_load(p, __ATOMIC_RELAXED, __HIP_MEMORY_SCOPE_AGENT); }
; #define XB_SPIN(cond, bar) do { unsigned _sp = 0; while (cond) { __builtin_amdgcn_s_sleep(1); \
;     if ((++_sp & 255u) == 0u) { if (xb_ld(&(bar)[XB_TMO])) break; if (_sp > XB_SPIN_CAP) { atomicAdd(&(bar)[XB_TMO], 1u); break; } } } } while (0)
; __device__ __forceinline__ void xcd_barrier(const XcdBarrier& b, const bool local_only = false) {
;     ...
;         } else {
;             XB_SPIN(xb_ld(&bar[XB_XGEN(b.x)]) == gen, bar);
;             __builtin_amdgcn_fence(__ATOMIC_ACQUIRE, "agent");
;             asm volatile("s_waitcnt vmcnt(0)" ::: "memory");
;         }
.LBB0_566:
	s_or_b64 exec, exec, s[20:21]
.Lxb_arr_3:
	s_waitcnt vmcnt(0) lgkmcnt(0)
	v_readlane_b32 vcc_lo, v253, 2
	v_readlane_b32 vcc_hi, v253, 3
	s_nop 0
	s_and_b64 vcc, exec, vcc
	s_cbranch_vccz .Lxb_nl_skip_5
	buffer_inv sc1
.Lxb_nl_skip_5:
	s_waitcnt vmcnt(0)

; __device__ __forceinline__ unsigned xb_ld(unsigned* p)              { return __hip_atomic_load(p, __ATOMIC_RELAXED, __HIP_MEMORY_SCOPE_AGENT); }
; __device__ __forceinline__ unsigned xb_add(unsigned* p, unsigned v) { return __hip_atomic_fetch_add(p, v, __ATOMIC_RELAXED, __HIP_MEMORY_SCOPE_AGENT); }
; #define XB_SPIN(cond, bar) do { unsigned _sp = 0; while (cond) { __builtin_amdgcn_s_sleep(1); \
;     if ((++_sp & 255u) == 0u) { if (xb_ld(&(bar)[XB_TMO])) break; if (_sp > XB_SPIN_CAP) { atomicAdd(&(bar)[XB_TMO], 1u); break; } } } } while (0)
; __device__ __forceinline__ void xcd_barrier(const XcdBarrier& b, const bool local_only = false) {
;     ...
;         const unsigned old = xb_add(&bar[XB_XSUB(b.x)], 1u);
;         const unsigned gen = old / nloc;
;         if (old + 1u == (gen + 1u) * nloc) {
;             if (!local_only) {
;             __builtin_amdgcn_fence(__ATOMIC_RELEASE, "agent");
;             asm volatile("s_waitcnt vmcnt(0)" ::: "memory");
;             const unsigned og = xb_add(&bar[XB_TOP], 1u);
;             const unsigned tg = og / nx;
;             if (og + 1u == (tg + 1u) * nx) xb_add(&bar[XB_TOPGEN], 1u);
;             else XB_SPIN(xb_ld(&bar[XB_TOPGEN]) == tg, bar);
;             }
;             __builtin_amdgcn_fence(__ATOMIC_ACQUIRE, "agent");
;             xb_add(&bar[XB_XGEN(b.x)], 1u);
;             asm volatile("s_waitcnt vmcnt(0)" ::: "memory");
;         } else {
;             XB_SPIN(xb_ld(&bar[XB_XGEN(b.x)]) == gen, bar);
.LBB0_674:
	s_or_b64 exec, exec, s[12:13]
	buffer_inv sc1
	v_cvt_f32_u32_e32 v3, v0
	s_waitcnt vmcnt(0)
	v_readfirstlane_b32 s6, v2
	v_sub_u32_e32 v2, 0, v0
	v_rcp_iflag_f32_e32 v3, v3
	v_add_u32_e32 v4, s6, v1
	v_mul_f32_e32 v3, 0x4f7ffffe, v3
	v_cvt_u32_f32_e32 v3, v3
	v_mul_lo_u32 v1, v2, v3
	v_mul_hi_u32 v1, v3, v1
	v_add_u32_e32 v1, v3, v1
	v_mul_hi_u32 v1, v4, v1
	v_mul_lo_u32 v2, v1, v0
	v_sub_u32_e32 v2, v4, v2
	v_add_u32_e32 v3, 1, v1
	v_cmp_ge_u32_e32 vcc, v2, v0
	s_nop 1
	v_cndmask_b32_e32 v1, v1, v3, vcc
	v_sub_u32_e32 v3, v2, v0
	v_cndmask_b32_e32 v2, v2, v3, vcc
	v_add_u32_e32 v3, 1, v1
	v_cmp_ge_u32_e32 vcc, v2, v0
	v_add_u32_e32 v2, 1, v4
	s_nop 0
	v_cndmask_b32_e32 v1, v1, v3, vcc
	v_mul_lo_u32 v3, v0, v1
	v_add_u32_e32 v0, v3, v0
	v_cmp_ne_u32_e32 vcc, v2, v0
	s_and_saveexec_b64 s[6:7], vcc
	s_xor_b64 s[6:7], exec, s[6:7]
	s_cbranch_execz .LBB0_688
	v_readlane_b32 vcc_lo, v253, 2
	v_readlane_b32 vcc_hi, v253, 3
	s_nop 0
	s_and_b64 vcc, exec, vcc
	s_cbranch_vccnz .Lxb_gen_4
	v_mov_b32_e32 v4, v0
	v_mov_b32_e32 v5, 0x1000
	s_mov_b32 s18, 0

; __device__ __forceinline__ unsigned xb_ld(unsigned* p)              { return __hip_atomic_load(p, __ATOMIC_RELAXED, __HIP_MEMORY_SCOPE_AGENT); }
; #define XB_SPIN(cond, bar) do { unsigned _sp = 0; while (cond) { __builtin_amdgcn_s_sleep(1); \
;     if ((++_sp & 255u) == 0u) { if (xb_ld(&(bar)[XB_TMO])) break; if (_sp > XB_SPIN_CAP) { atomicAdd(&(bar)[XB_TMO], 1u); break; } } } } while (0)
; __device__ __forceinline__ void xcd_barrier(const XcdBarrier& b, const bool local_only = false) {
;     ...
;         } else {
;             XB_SPIN(xb_ld(&bar[XB_XGEN(b.x)]) == gen, bar);
;             __builtin_amdgcn_fence(__ATOMIC_ACQUIRE, "agent");
;             asm volatile("s_waitcnt vmcnt(0)" ::: "memory");
.Lxb_gen_4:
	v_mov_b32_e32 v0, 0x2000
	global_load_dword v0, v0, s[4:5] offset:1024 sc1
	s_add_u32 s18, s4, 0x2400
	s_addc_u32 s19, s5, 0
	s_waitcnt vmcnt(0)
	v_cmp_eq_u32_e32 vcc, v0, v1
	s_and_saveexec_b64 s[12:13], vcc
	s_cbranch_execz .LBB0_687
	s_add_u32 s14, s8, 0x1200
	s_addc_u32 s15, s9, 0
	s_mov_b32 s38, 1
	s_mov_b64 s[20:21], 0
	s_branch .LBB0_678

; __device__ __forceinline__ unsigned xb_ld(unsigned* p)              { return __hip_atomic_load(p, __ATOMIC_RELAXED, __HIP_MEMORY_SCOPE_AGENT); }
; #define XB_SPIN(cond, bar) do { unsigned _sp = 0; while (cond) { __builtin_amdgcn_s_sleep(1); \
;     if ((++_sp & 255u) == 0u) { if (xb_ld(&(bar)[XB_TMO])) break; if (_sp > XB_SPIN_CAP) { atomicAdd(&(bar)[XB_TMO], 1u); break; } } } } while (0)
; __device__ __forceinline__ void xcd_barrier(const XcdBarrier& b, const bool local_only = false) {
;     ...
;         } else {
;             XB_SPIN(xb_ld(&bar[XB_XGEN(b.x)]) == gen, bar);
;             __builtin_amdgcn_fence(__ATOMIC_ACQUIRE, "agent");
;             asm volatile("s_waitcnt vmcnt(0)" ::: "memory");
;         }
.LBB0_687:
	s_or_b64 exec, exec, s[12:13]
.Lxb_arr_4:
	s_waitcnt vmcnt(0) lgkmcnt(0)
	v_readlane_b32 vcc_lo, v253, 2
	v_readlane_b32 vcc_hi, v253, 3
	s_nop 0
	s_and_b64 vcc, exec, vcc
	s_cbranch_vccz .Lxb_nl_skip_7
	buffer_inv sc1
.Lxb_nl_skip_7:
	s_waitcnt vmcnt(0)

; #define LAS __attribute__((address_space(3)))
; __device__ __forceinline__ unsigned pk2(float lo, float hi) { return f2bf(lo) | (f2bf(hi) << 16); }
; #define ws KWS(F)
; __device__ __forceinline__ void spatial_phase(const Frame& F, bf16* Z, const float* stats, const float* lng, const float* lnb, const float* ws, const float* bs, bool do_store = true) {
;     ...
;         if (g != staged_g) { staged_g = g; const float* wg = ws + (size_t)g * 128 * 128;
; #pragma unroll
;             for (int i = 0; i < 8; ++i) { const int p = tid + 512 * i, t = p >> 5, s4 = (p & 31) * 4; f32x4 x = *(const f32x4*)(wg + t * 128 + s4);
;                 if (s4 + 0 > t) x.x = 0.f; if (s4 + 1 > t) x.y = 0.f; if (s4 + 2 > t) x.z = 0.f; if (s4 + 3 > t) x.w = 0.f;
;                 *(LAS v2u*)(Wl + t * LST + s4 * 2) = (v2u){pk2(x.x, x.y), pk2(x.z, x.w)}; } }
.LBB0_721:
	s_or_b64 exec, exec, s[14:15]
	s_cmp_eq_u32 s45, s46
	s_cbranch_scc1 .LBB0_723
	s_lshl_b32 s48, s45, 16
	v_lshl_add_u64 v[96:97], v[162:163], 0, s[48:49]
	v_lshl_add_u64 v[98:99], v[146:147], 2, v[96:97]
	global_load_dwordx4 v[0:3], v[98:99], off
	v_lshl_add_u64 v[98:99], v[148:149], 2, v[96:97]
	global_load_dwordx4 v[4:7], v[98:99], off
	v_lshl_add_u64 v[98:99], v[150:151], 2, v[96:97]
	global_load_dwordx4 v[8:11], v[98:99], off
	v_lshl_add_u64 v[98:99], v[152:153], 2, v[96:97]
	global_load_dwordx4 v[12:15], v[98:99], off
	v_lshl_add_u64 v[98:99], v[154:155], 2, v[96:97]
	global_load_dwordx4 v[16:19], v[98:99], off
	v_lshl_add_u64 v[98:99], v[156:157], 2, v[96:97]
	global_load_dwordx4 v[20:23], v[98:99], off
	v_lshl_add_u64 v[98:99], v[158:159], 2, v[96:97]
	global_load_dwordx4 v[24:27], v[98:99], off
	v_lshl_add_u64 v[98:99], v[160:161], 2, v[96:97]
	global_load_dwordx4 v[28:31], v[98:99], off
	v_readlane_b32 s12, v255, 12
	v_mov_b32_e32 v102, s49
	v_readlane_b32 s13, v255, 13
	s_mov_b32 s46, s45
	s_waitcnt vmcnt(7)
	v_cndmask_b32_e64 v1, 0, v1, s[42:43]
	v_cndmask_b32_e64 v102, v0, v102, s[12:13]
	v_cndmask_b32_e64 v0, v102, v0, s[42:43]
	v_readlane_b32 s12, v255, 14
	v_readlane_b32 s13, v255, 15
	v_bfe_u32 v102, v0, 16, 1
	v_add3_u32 v0, v0, v102, s37
	v_cndmask_b32_e64 v2, v2, 0, s[12:13]
	v_readlane_b32 s12, v255, 16
	v_bfe_u32 v102, v1, 16, 1
	v_readlane_b32 s13, v255, 17
	v_lshrrev_b32_e32 v0, 16, v0
	v_add3_u32 v1, v1, v102, s37
	v_cndmask_b32_e64 v3, v3, 0, s[12:13]
	v_and_or_b32 v0, v1, s68, v0
	v_bfe_u32 v1, v2, 16, 1
	v_add3_u32 v1, v2, v1, s37
	v_bfe_u32 v2, v3, 16, 1
	v_lshrrev_b32_e32 v1, 16, v1
	v_add3_u32 v2, v3, v2, s37
	v_and_or_b32 v1, v2, s68, v1
	ds_write_b64 v234, v[0:1]
	v_mov_b32_e32 v102, s49
	s_waitcnt vmcnt(6)
	v_cndmask_b32_e64 v102, v4, v102, s[24:25]
	v_cndmask_b32_e64 v4, v102, v4, s[50:51]
	v_cndmask_b32_e64 v5, 0, v5, s[50:51]
	v_bfe_u32 v102, v4, 16, 1
	v_add3_u32 v4, v4, v102, s37
	v_bfe_u32 v102, v5, 16, 1
	v_cndmask_b32_e64 v6, v6, 0, s[52:53]
	v_lshrrev_b32_e32 v4, 16, v4
	v_add3_u32 v5, v5, v102, s37
	v_cndmask_b32_e64 v7, v7, 0, s[54:55]
	v_and_or_b32 v4, v5, s68, v4
	v_bfe_u32 v5, v6, 16, 1
	v_add3_u32 v5, v6, v5, s37
	v_bfe_u32 v6, v7, 16, 1
	v_lshrrev_b32_e32 v5, 16, v5
	v_add3_u32 v6, v7, v6, s37
	v_and_or_b32 v5, v6, s68, v5
	ds_write_b64 v203, v[4:5]
	v_mov_b32_e32 v102, s49
	s_waitcnt vmcnt(5)
	v_cndmask_b32_e64 v102, v8, v102, s[56:57]
	v_cndmask_b32_e64 v8, v102, v8, s[58:59]
	v_cndmask_b32_e64 v9, 0, v9, s[58:59]
	v_bfe_u32 v102, v8, 16, 1
	v_add3_u32 v8, v8, v102, s37
	v_bfe_u32 v102, v9, 16, 1
	v_cndmask_b32_e64 v10, v10, 0, s[60:61]
	v_lshrrev_b32_e32 v8, 16, v8
	v_add3_u32 v9, v9, v102, s37
	v_cndmask_b32_e64 v11, v11, 0, s[62:63]
	v_and_or_b32 v8, v9, s68, v8
	v_bfe_u32 v9, v10, 16, 1
	v_add3_u32 v9, v10, v9, s37
	v_bfe_u32 v10, v11, 16, 1
	v_lshrrev_b32_e32 v9, 16, v9
	v_add3_u32 v10, v11, v10, s37
	v_and_or_b32 v9, v10, s68, v9
	ds_write_b64 v235, v[8:9]
	v_mov_b32_e32 v102, s49
	s_waitcnt vmcnt(4)
	v_cndmask_b32_e64 v102, v12, v102, s[64:65]
	v_cndmask_b32_e64 v12, v102, v12, s[66:67]
	v_cndmask_b32_e64 v13, 0, v13, s[66:67]
	v_bfe_u32 v102, v12, 16, 1
	v_add3_u32 v12, v12, v102, s37
	v_bfe_u32 v102, v13, 16, 1
	v_cndmask_b32_e64 v14, v14, 0, s[40:41]
	v_lshrrev_b32_e32 v12, 16, v12
	v_add3_u32 v13, v13, v102, s37
	v_cndmask_b32_e64 v15, v15, 0, s[70:71]
	v_and_or_b32 v12, v13, s68, v12
	v_bfe_u32 v13, v14, 16, 1
	v_add3_u32 v13, v14, v13, s37
	v_bfe_u32 v14, v15, 16, 1
	v_lshrrev_b32_e32 v13, 16, v13
	v_add3_u32 v14, v15, v14, s37
	v_and_or_b32 v13, v14, s68, v13
	ds_write_b64 v196, v[12:13]
	v_mov_b32_e32 v102, s49
	s_waitcnt vmcnt(3)
	v_cndmask_b32_e64 v102, v16, v102, s[72:73]
	v_cndmask_b32_e64 v16, v102, v16, s[74:75]
	v_cndmask_b32_e64 v17, 0, v17, s[74:75]
	v_bfe_u32 v102, v16, 16, 1
	v_add3_u32 v16, v16, v102, s37
	v_bfe_u32 v102, v17, 16, 1
	v_cndmask_b32_e64 v18, v18, 0, s[76:77]
	v_lshrrev_b32_e32 v16, 16, v16
	v_add3_u32 v17, v17, v102, s37
	v_cndmask_b32_e64 v19, v19, 0, s[78:79]
	v_and_or_b32 v16, v17, s68, v16
	v_bfe_u32 v17, v18, 16, 1
	v_add3_u32 v17, v18, v17, s37
	v_bfe_u32 v18, v19, 16, 1
	v_lshrrev_b32_e32 v17, 16, v17
	v_add3_u32 v18, v19, v18, s37
	v_and_or_b32 v17, v18, s68, v17
	ds_write_b64 v197, v[16:17]
	v_mov_b32_e32 v102, s49
	s_waitcnt vmcnt(2)
	v_cndmask_b32_e64 v102, v20, v102, s[80:81]
	v_cndmask_b32_e64 v20, v102, v20, s[82:83]
	v_cndmask_b32_e64 v21, 0, v21, s[82:83]
	v_bfe_u32 v102, v20, 16, 1
	v_add3_u32 v20, v20, v102, s37
	v_bfe_u32 v102, v21, 16, 1
	v_cndmask_b32_e64 v22, v22, 0, s[84:85]
	v_lshrrev_b32_e32 v20, 16, v20
	v_add3_u32 v21, v21, v102, s37
	v_cndmask_b32_e64 v23, v23, 0, s[86:87]
	v_and_or_b32 v20, v21, s68, v20
	v_bfe_u32 v21, v22, 16, 1
	v_add3_u32 v21, v22, v21, s37
	v_bfe_u32 v22, v23, 16, 1
	v_lshrrev_b32_e32 v21, 16, v21
	v_add3_u32 v22, v23, v22, s37
	v_and_or_b32 v21, v22, s68, v21
	ds_write_b64 v198, v[20:21]
	v_mov_b32_e32 v102, s49
	s_waitcnt vmcnt(1)
	v_cndmask_b32_e64 v102, v24, v102, s[88:89]
	v_cndmask_b32_e64 v24, v102, v24, s[90:91]
	v_cndmask_b32_e64 v25, 0, v25, s[90:91]
	v_bfe_u32 v102, v24, 16, 1
	v_add3_u32 v24, v24, v102, s37
	v_bfe_u32 v102, v25, 16, 1
	v_cndmask_b32_e64 v26, v26, 0, s[92:93]
	v_lshrrev_b32_e32 v24, 16, v24
	v_add3_u32 v25, v25, v102, s37
	v_cndmask_b32_e64 v27, v27, 0, s[94:95]
	v_and_or_b32 v24, v25, s68, v24
	v_bfe_u32 v25, v26, 16, 1
	v_add3_u32 v25, v26, v25, s37
	v_bfe_u32 v26, v27, 16, 1
	v_lshrrev_b32_e32 v25, 16, v25
	v_add3_u32 v26, v27, v26, s37
	v_and_or_b32 v25, v26, s68, v25
	ds_write_b64 v199, v[24:25]
	v_mov_b32_e32 v100, s49
	s_waitcnt vmcnt(0)
	v_cndmask_b32_e64 v100, v28, v100, s[96:97]
	v_cndmask_b32_e64 v28, v100, v28, s[4:5]
	v_cndmask_b32_e64 v29, 0, v29, s[4:5]
	v_bfe_u32 v100, v28, 16, 1
	v_add3_u32 v28, v28, v100, s37
	v_bfe_u32 v100, v29, 16, 1
	v_cndmask_b32_e64 v30, v30, 0, s[6:7]
	v_lshrrev_b32_e32 v28, 16, v28
	v_add3_u32 v29, v29, v100, s37
	v_cndmask_b32_e64 v31, v31, 0, s[8:9]
	v_and_or_b32 v28, v29, s68, v28
	v_bfe_u32 v29, v30, 16, 1
	v_add3_u32 v29, v30, v29, s37
	v_bfe_u32 v30, v31, 16, 1
	v_lshrrev_b32_e32 v29, 16, v29
	v_add3_u32 v30, v31, v30, s37
	v_and_or_b32 v29, v30, s68, v29
	ds_write_b64 v200, v[28:29]
; #define LAS __attribute__((address_space(3)))
; __device__ __forceinline__ unsigned pk2(float lo, float hi) { return f2bf(lo) | (f2bf(hi) << 16); }
; __device__ __forceinline__ float bflo(unsigned w) { return __uint_as_float(w << 16); }
; __device__ __forceinline__ float bfhi(unsigned w) { return __uint_as_float(w & 0xffff0000u); }
; __device__ __forceinline__ void spatial_phase(const Frame& F, bf16* Z, const float* stats, const float* lng, const float* lnb, const float* ws, const float* bs, bool do_store = true) {
;     ...
;         {
;             const float meanA = st[4 * lane], rstdA = st[4 * lane + 1], meanB = st[4 * lane + 2], rstdB = st[4 * lane + 3];
; #pragma unroll
;             for (int it = 0; it < 4; ++it) { const int c0 = 32 * w + 8 * it;
;                 const f32x4 ga = *(const f32x4*)(lng + 256 * g + c0), gb = *(const f32x4*)(lng + 256 * g + c0 + 4), ba = *(const f32x4*)(lnb + 256 * g + c0), bb = *(const f32x4*)(lnb + 256 * g + c0 + 4);
;                 const float lg[8] = {ga.x, ga.y, ga.z, ga.w, gb.x, gb.y, gb.z, gb.w}, lb[8] = {ba.x, ba.y, ba.z, ba.w, bb.x, bb.y, bb.z, bb.w};
; #pragma unroll
;                 for (int e = 0; e < 8; ++e) { const unsigned wa = rawA[it][e >> 1], wb = rawB[it][e >> 1]; const float xa = (e & 1) ? bfhi(wa) : bflo(wa), xb = (e & 1) ? bfhi(wb) : bflo(wb);
;                     const float ya = (xa - meanA) * rstdA * lg[e] + lb[e], yb = (xb - meanB) * rstdB * lg[e] + lb[e];
;                     *(LAS unsigned*)(Vt + (c0 + e) * LST + 4 * lane) = pk2(ya, yb); } } }
.LBB0_723:
	s_lshl_b32 s12, s45, 8
	s_lshl_b32 s13, s12, 2
	v_mov_b32_e32 v223, s13
	s_waitcnt lgkmcnt(0)
	s_barrier
	ds_read_b128 v[96:99], v133
	global_load_dwordx4 v[104:107], v223, s[20:21] offset:48
	global_load_dwordx4 v[116:119], v223, s[20:21] offset:32
	global_load_dwordx4 v[124:127], v223, s[20:21] offset:16
	global_load_dwordx4 v[128:131], v223, s[20:21]
	global_load_dwordx4 v[100:103], v223, s[0:1] offset:48
	global_load_dwordx4 v[108:111], v223, s[0:1] offset:32
	global_load_dwordx4 v[120:123], v223, s[0:1] offset:16
	global_load_dwordx4 v[224:227], v223, s[0:1]
	s_waitcnt vmcnt(29)
	v_lshlrev_b32_e32 v138, 16, v88
	s_waitcnt vmcnt(28)
	v_lshlrev_b32_e32 v139, 16, v92
	v_and_b32_e32 v88, 0xffff0000, v88
	s_waitcnt lgkmcnt(0)
	v_sub_f32_e32 v138, v138, v96
	v_mul_f32_e32 v138, v97, v138
	v_sub_f32_e32 v139, v139, v98
	v_and_b32_e32 v92, 0xffff0000, v92
	v_sub_f32_e32 v88, v88, v96
	v_mul_f32_e32 v139, v99, v139
	v_mul_f32_e32 v88, v97, v88
	v_sub_f32_e32 v92, v92, v98
	v_mul_f32_e32 v92, v99, v92
	v_readlane_b32 s13, v254, 22
	v_readlane_b32 s14, v254, 16
	v_readlane_b32 s15, v254, 17
	s_andn2_b64 vcc, exec, s[14:15]
	s_waitcnt vmcnt(0)
	v_fma_f32 v138, v138, v128, v224
	v_fma_f32 v128, v139, v128, v224
	v_bfe_u32 v139, v138, 16, 1
	v_fma_f32 v88, v88, v129, v225
	v_add3_u32 v138, v138, v139, s37
	v_bfe_u32 v139, v128, 16, 1
	v_fma_f32 v92, v92, v129, v225
	v_bfe_u32 v129, v88, 16, 1
	v_lshrrev_b32_e32 v138, 16, v138
	v_add3_u32 v128, v128, v139, s37
	v_add3_u32 v88, v88, v129, s37
	v_bfe_u32 v129, v92, 16, 1
	v_and_or_b32 v138, v128, s68, v138
	v_add_u32_e32 v128, s13, v137
	v_lshrrev_b32_e32 v88, 16, v88
	v_add3_u32 v92, v92, v129, s37
	v_and_or_b32 v88, v92, s68, v88
	v_add_u32_e32 v92, 0x8800, v128
	ds_write2_b32 v92, v138, v88 offset1:68
	v_lshlrev_b32_e32 v88, 16, v89
	v_and_b32_e32 v89, 0xffff0000, v89
	v_lshlrev_b32_e32 v129, 16, v93
	v_sub_f32_e32 v88, v88, v96
	v_and_b32_e32 v93, 0xffff0000, v93
	v_sub_f32_e32 v89, v89, v96
	v_mul_f32_e32 v88, v97, v88
	v_sub_f32_e32 v129, v129, v98
	v_mul_f32_e32 v89, v97, v89
	v_sub_f32_e32 v93, v93, v98
	v_fma_f32 v88, v88, v130, v226
	v_mul_f32_e32 v129, v99, v129
	v_fma_f32 v89, v89, v131, v227
	v_mul_f32_e32 v93, v99, v93
	v_fma_f32 v129, v129, v130, v226
	v_bfe_u32 v130, v88, 16, 1
	v_fmac_f32_e32 v227, v93, v131
	v_bfe_u32 v93, v89, 16, 1
	v_add3_u32 v88, v88, v130, s37
	v_bfe_u32 v130, v129, 16, 1
	v_add3_u32 v89, v89, v93, s37
	v_bfe_u32 v93, v227, 16, 1
	v_lshrrev_b32_e32 v88, 16, v88
	v_add3_u32 v129, v129, v130, s37
	v_lshrrev_b32_e32 v89, 16, v89
	v_add3_u32 v93, v227, v93, s37
	v_and_or_b32 v88, v129, s68, v88
	v_and_or_b32 v89, v93, s68, v89
	ds_write2_b32 v92, v88, v89 offset0:136 offset1:204
	v_lshlrev_b32_e32 v88, 16, v90
	v_lshlrev_b32_e32 v89, 16, v94
	v_sub_f32_e32 v88, v88, v96
	v_mul_f32_e32 v88, v97, v88
	v_sub_f32_e32 v89, v89, v98
	v_fma_f32 v88, v88, v124, v120
	v_mul_f32_e32 v89, v99, v89
	v_fma_f32 v89, v89, v124, v120
	v_bfe_u32 v92, v88, 16, 1
	v_add3_u32 v88, v88, v92, s37
	v_bfe_u32 v92, v89, 16, 1
	v_lshrrev_b32_e32 v88, 16, v88
	v_add3_u32 v89, v89, v92, s37
	v_and_or_b32 v88, v89, s68, v88
	v_and_b32_e32 v89, 0xffff0000, v90
	v_and_b32_e32 v90, 0xffff0000, v94
	v_sub_f32_e32 v89, v89, v96
	v_mul_f32_e32 v89, v97, v89
	v_sub_f32_e32 v90, v90, v98
	v_fma_f32 v89, v89, v125, v121
	v_mul_f32_e32 v90, v99, v90
	v_fma_f32 v90, v90, v125, v121
	v_bfe_u32 v92, v89, 16, 1
	v_add3_u32 v89, v89, v92, s37
	v_bfe_u32 v92, v90, 16, 1
	v_lshrrev_b32_e32 v89, 16, v89
	v_add3_u32 v90, v90, v92, s37
	v_and_or_b32 v89, v90, s68, v89
	v_add_u32_e32 v90, 0x8c00, v128
	ds_write2_b32 v90, v88, v89 offset0:16 offset1:84
	v_lshlrev_b32_e32 v88, 16, v91
	v_lshlrev_b32_e32 v89, 16, v95
	v_sub_f32_e32 v88, v88, v96
	v_mul_f32_e32 v88, v97, v88
	v_sub_f32_e32 v89, v89, v98
	v_fma_f32 v88, v88, v126, v122
	v_mul_f32_e32 v89, v99, v89
	v_fma_f32 v89, v89, v126, v122
	v_bfe_u32 v92, v88, 16, 1
	v_add3_u32 v88, v88, v92, s37
	v_bfe_u32 v92, v89, 16, 1
	v_lshrrev_b32_e32 v88, 16, v88
	v_add3_u32 v89, v89, v92, s37
	v_and_or_b32 v88, v89, s68, v88
	v_and_b32_e32 v89, 0xffff0000, v91
	v_and_b32_e32 v91, 0xffff0000, v95
	v_sub_f32_e32 v89, v89, v96
	v_mul_f32_e32 v89, v97, v89
	v_sub_f32_e32 v91, v91, v98
	v_fma_f32 v89, v89, v127, v123
	v_mul_f32_e32 v91, v99, v91
	v_fmac_f32_e32 v123, v91, v127
	v_bfe_u32 v91, v89, 16, 1
	v_add3_u32 v89, v89, v91, s37
	v_bfe_u32 v91, v123, 16, 1
	v_lshrrev_b32_e32 v89, 16, v89
	v_add3_u32 v91, v123, v91, s37
	v_and_or_b32 v89, v91, s68, v89
	ds_write2_b32 v90, v88, v89 offset0:152 offset1:220
	v_lshlrev_b32_e32 v88, 16, v80
	v_lshlrev_b32_e32 v89, 16, v84
	v_sub_f32_e32 v88, v88, v96
	v_mul_f32_e32 v88, v97, v88
	v_sub_f32_e32 v89, v89, v98
	v_fma_f32 v88, v88, v116, v108
	v_mul_f32_e32 v89, v99, v89
	v_fma_f32 v89, v89, v116, v108
	v_bfe_u32 v90, v88, 16, 1
	v_and_b32_e32 v80, 0xffff0000, v80
	v_add3_u32 v88, v88, v90, s37
	v_bfe_u32 v90, v89, 16, 1
	v_and_b32_e32 v84, 0xffff0000, v84
	v_sub_f32_e32 v80, v80, v96
	v_lshrrev_b32_e32 v88, 16, v88
	v_add3_u32 v89, v89, v90, s37
	v_readlane_b32 s13, v254, 23
	v_mul_f32_e32 v80, v97, v80
	v_sub_f32_e32 v84, v84, v98
	v_and_or_b32 v88, v89, s68, v88
	v_add_u32_e32 v120, s13, v137
	v_fma_f32 v80, v80, v117, v109
	v_mul_f32_e32 v84, v99, v84
	ds_write_b32 v120, v88 offset:34816
	v_fma_f32 v84, v84, v117, v109
	v_bfe_u32 v88, v80, 16, 1
	v_add3_u32 v80, v80, v88, s37
	v_bfe_u32 v88, v84, 16, 1
	v_lshrrev_b32_e32 v80, 16, v80
	v_add3_u32 v84, v84, v88, s37
	v_and_or_b32 v80, v84, s68, v80
	v_lshlrev_b32_e32 v84, 16, v81
	v_lshlrev_b32_e32 v88, 16, v85
	v_sub_f32_e32 v84, v84, v96
	v_mul_f32_e32 v84, v97, v84
; #define LAS __attribute__((address_space(3)))
; __device__ __forceinline__ unsigned pk2(float lo, float hi) { return f2bf(lo) | (f2bf(hi) << 16); }
; __device__ __forceinline__ float bflo(unsigned w) { return __uint_as_float(w << 16); }
; __device__ __forceinline__ float bfhi(unsigned w) { return __uint_as_float(w & 0xffff0000u); }
; __device__ __forceinline__ void spatial_phase(const Frame& F, bf16* Z, const float* stats, const float* lng, const float* lnb, const float* ws, const float* bs, bool do_store = true) {
;     ...
;             for (int it = 0; it < 4; ++it) { const int c0 = 32 * w + 8 * it;
;                 const f32x4 ga = *(const f32x4*)(lng + 256 * g + c0), gb = *(const f32x4*)(lng + 256 * g + c0 + 4), ba = *(const f32x4*)(lnb + 256 * g + c0), bb = *(const f32x4*)(lnb + 256 * g + c0 + 4);
;                 const float lg[8] = {ga.x, ga.y, ga.z, ga.w, gb.x, gb.y, gb.z, gb.w}, lb[8] = {ba.x, ba.y, ba.z, ba.w, bb.x, bb.y, bb.z, bb.w};
; #pragma unroll
;                 for (int e = 0; e < 8; ++e) { const unsigned wa = rawA[it][e >> 1], wb = rawB[it][e >> 1]; const float xa = (e & 1) ? bfhi(wa) : bflo(wa), xb = (e & 1) ? bfhi(wb) : bflo(wb);
;                     const float ya = (xa - meanA) * rstdA * lg[e] + lb[e], yb = (xb - meanB) * rstdB * lg[e] + lb[e];
;                     *(LAS unsigned*)(Vt + (c0 + e) * LST + 4 * lane) = pk2(ya, yb); } } }
	v_sub_f32_e32 v88, v88, v98
	v_fma_f32 v84, v84, v118, v110
	v_mul_f32_e32 v88, v99, v88
	v_fma_f32 v88, v88, v118, v110
	v_bfe_u32 v89, v84, 16, 1
	v_add3_u32 v84, v84, v89, s37
	v_bfe_u32 v89, v88, 16, 1
	v_lshrrev_b32_e32 v84, 16, v84
	v_add3_u32 v88, v88, v89, s37
	v_and_or_b32 v84, v88, s68, v84
	v_add_u32_e32 v88, 0x9000, v128
	ds_write2_b32 v88, v80, v84 offset0:100 offset1:168
	v_and_b32_e32 v80, 0xffff0000, v81
	v_and_b32_e32 v81, 0xffff0000, v85
	v_sub_f32_e32 v80, v80, v96
	v_mul_f32_e32 v80, v97, v80
	v_sub_f32_e32 v81, v81, v98
	v_fma_f32 v80, v80, v119, v111
	v_mul_f32_e32 v81, v99, v81
	v_fmac_f32_e32 v111, v81, v119
	v_bfe_u32 v81, v80, 16, 1
	v_add3_u32 v80, v80, v81, s37
	v_bfe_u32 v81, v111, 16, 1
	v_lshrrev_b32_e32 v80, 16, v80
	v_add3_u32 v81, v111, v81, s37
	v_and_or_b32 v80, v81, s68, v80
	v_lshlrev_b32_e32 v81, 16, v82
	v_lshlrev_b32_e32 v84, 16, v86
	v_sub_f32_e32 v81, v81, v96
	v_mul_f32_e32 v81, v97, v81
	v_sub_f32_e32 v84, v84, v98
	v_fma_f32 v81, v81, v104, v100
	v_mul_f32_e32 v84, v99, v84
	v_fma_f32 v84, v84, v104, v100
	v_bfe_u32 v85, v81, 16, 1
	v_add3_u32 v81, v81, v85, s37
	v_bfe_u32 v85, v84, 16, 1
	v_lshrrev_b32_e32 v81, 16, v81
	v_add3_u32 v84, v84, v85, s37
	v_and_or_b32 v81, v84, s68, v81
	v_add_u32_e32 v84, 0x9200, v128
	ds_write2_b32 v84, v80, v81 offset0:108 offset1:176
	v_and_b32_e32 v80, 0xffff0000, v82
	v_and_b32_e32 v81, 0xffff0000, v86
	v_sub_f32_e32 v80, v80, v96
	v_mul_f32_e32 v80, v97, v80
	v_sub_f32_e32 v81, v81, v98
	v_fma_f32 v80, v80, v105, v101
	v_mul_f32_e32 v81, v99, v81
	v_fma_f32 v81, v81, v105, v101
	v_bfe_u32 v82, v80, 16, 1
	v_add3_u32 v80, v80, v82, s37
	v_bfe_u32 v82, v81, 16, 1
	v_lshrrev_b32_e32 v80, 16, v80
	v_add3_u32 v81, v81, v82, s37
	v_and_or_b32 v80, v81, s68, v80
	v_lshlrev_b32_e32 v81, 16, v83
	v_lshlrev_b32_e32 v82, 16, v87
	v_sub_f32_e32 v81, v81, v96
	v_mul_f32_e32 v81, v97, v81
	v_sub_f32_e32 v82, v82, v98
	v_fma_f32 v81, v81, v106, v102
	v_mul_f32_e32 v82, v99, v82
	v_fma_f32 v82, v82, v106, v102
	v_bfe_u32 v84, v81, 16, 1
	v_add3_u32 v81, v81, v84, s37
	v_bfe_u32 v84, v82, 16, 1
	v_lshrrev_b32_e32 v81, 16, v81
	v_add3_u32 v82, v82, v84, s37
	v_and_or_b32 v81, v82, s68, v81
	v_add_u32_e32 v82, 0x9400, v128
	ds_write2_b32 v82, v80, v81 offset0:116 offset1:184
	v_and_b32_e32 v80, 0xffff0000, v83
	v_and_b32_e32 v81, 0xffff0000, v87
	v_sub_f32_e32 v80, v80, v96
	v_mul_f32_e32 v80, v97, v80
	v_sub_f32_e32 v81, v81, v98
	v_fma_f32 v80, v80, v107, v103
	v_mul_f32_e32 v81, v99, v81
	v_fmac_f32_e32 v103, v81, v107
	v_bfe_u32 v81, v80, 16, 1
	v_add3_u32 v80, v80, v81, s37
	v_bfe_u32 v81, v103, 16, 1
	v_lshrrev_b32_e32 v80, 16, v80
	v_add3_u32 v81, v103, v81, s37
	v_and_or_b32 v121, v81, s68, v80
	global_load_dwordx4 v[80:83], v223, s[20:21] offset:112
	global_load_dwordx4 v[84:87], v223, s[20:21] offset:96
	global_load_dwordx4 v[88:91], v223, s[20:21] offset:80
	global_load_dwordx4 v[108:111], v223, s[20:21] offset:64
	global_load_dwordx4 v[92:95], v223, s[0:1] offset:112
	global_load_dwordx4 v[100:103], v223, s[0:1] offset:96
	global_load_dwordx4 v[104:107], v223, s[0:1] offset:80
	global_load_dwordx4 v[116:119], v223, s[0:1] offset:64
	v_lshlrev_b32_e32 v122, 16, v72
	v_lshlrev_b32_e32 v123, 16, v76
	v_sub_f32_e32 v122, v122, v96
	v_mul_f32_e32 v122, v97, v122
	v_sub_f32_e32 v123, v123, v98
	v_mul_f32_e32 v123, v99, v123
	v_and_b32_e32 v72, 0xffff0000, v72
	v_and_b32_e32 v76, 0xffff0000, v76
	v_sub_f32_e32 v72, v72, v96
	v_mul_f32_e32 v72, v97, v72
	v_sub_f32_e32 v76, v76, v98
	v_mul_f32_e32 v76, v99, v76
	s_waitcnt vmcnt(0)
	v_fma_f32 v122, v122, v108, v116
	v_fma_f32 v108, v123, v108, v116
	v_bfe_u32 v116, v122, 16, 1
	v_add3_u32 v116, v122, v116, s37
	v_bfe_u32 v122, v108, 16, 1
	v_lshrrev_b32_e32 v116, 16, v116
	v_add3_u32 v108, v108, v122, s37
	v_and_or_b32 v108, v108, s68, v116
	v_fma_f32 v72, v72, v109, v117
	ds_write_b32 v120, v108 offset:36992
	v_fma_f32 v76, v76, v109, v117
	v_bfe_u32 v108, v72, 16, 1
	v_add3_u32 v72, v72, v108, s37
	v_bfe_u32 v108, v76, 16, 1
	v_lshrrev_b32_e32 v72, 16, v72
	v_add3_u32 v76, v76, v108, s37
	v_and_or_b32 v72, v76, s68, v72
	v_add_u32_e32 v76, 0x9700, v128
	ds_write2_b32 v76, v121, v72 offset0:60 offset1:196
	v_lshlrev_b32_e32 v72, 16, v73
	v_lshlrev_b32_e32 v76, 16, v77
	v_sub_f32_e32 v72, v72, v96
	v_mul_f32_e32 v72, v97, v72
	v_sub_f32_e32 v76, v76, v98
	v_fma_f32 v72, v72, v110, v118
	v_mul_f32_e32 v76, v99, v76
	v_fma_f32 v76, v76, v110, v118
	v_bfe_u32 v108, v72, 16, 1
	v_add3_u32 v72, v72, v108, s37
	v_bfe_u32 v108, v76, 16, 1
	v_lshrrev_b32_e32 v72, 16, v72
	v_add3_u32 v76, v76, v108, s37
	v_and_b32_e32 v73, 0xffff0000, v73
	v_and_or_b32 v72, v76, s68, v72
	v_and_b32_e32 v76, 0xffff0000, v77
	v_sub_f32_e32 v73, v73, v96
	v_mul_f32_e32 v73, v97, v73
	v_sub_f32_e32 v76, v76, v98
	v_fma_f32 v73, v73, v111, v119
	v_mul_f32_e32 v76, v99, v76
	v_fmac_f32_e32 v119, v76, v111
	v_bfe_u32 v76, v73, 16, 1
	v_add3_u32 v73, v73, v76, s37
	v_bfe_u32 v76, v119, 16, 1
	v_lshrrev_b32_e32 v73, 16, v73
	v_add3_u32 v76, v119, v76, s37
	v_and_or_b32 v73, v76, s68, v73
	v_add_u32_e32 v76, 0x9a00, v128
	ds_write2_b32 v76, v72, v73 offset0:72 offset1:140
	v_lshlrev_b32_e32 v72, 16, v74
	v_lshlrev_b32_e32 v73, 16, v78
	v_sub_f32_e32 v72, v72, v96
	v_mul_f32_e32 v72, v97, v72
	v_sub_f32_e32 v73, v73, v98
	v_fma_f32 v72, v72, v88, v104
	v_mul_f32_e32 v73, v99, v73
	v_fma_f32 v73, v73, v88, v104
	v_bfe_u32 v76, v72, 16, 1
	v_add3_u32 v72, v72, v76, s37
	v_bfe_u32 v76, v73, 16, 1
	v_lshrrev_b32_e32 v72, 16, v72
	v_add3_u32 v73, v73, v76, s37
	v_and_or_b32 v72, v73, s68, v72
	v_and_b32_e32 v73, 0xffff0000, v74
	v_and_b32_e32 v74, 0xffff0000, v78
; #define LAS __attribute__((address_space(3)))
; __device__ __forceinline__ unsigned pk2(float lo, float hi) { return f2bf(lo) | (f2bf(hi) << 16); }
; __device__ __forceinline__ float bflo(unsigned w) { return __uint_as_float(w << 16); }
; __device__ __forceinline__ float bfhi(unsigned w) { return __uint_as_float(w & 0xffff0000u); }
; __device__ __forceinline__ void spatial_phase(const Frame& F, bf16* Z, const float* stats, const float* lng, const float* lnb, const float* ws, const float* bs, bool do_store = true) {
;     ...
;             for (int it = 0; it < 4; ++it) { const int c0 = 32 * w + 8 * it;
;                 const f32x4 ga = *(const f32x4*)(lng + 256 * g + c0), gb = *(const f32x4*)(lng + 256 * g + c0 + 4), ba = *(const f32x4*)(lnb + 256 * g + c0), bb = *(const f32x4*)(lnb + 256 * g + c0 + 4);
;                 const float lg[8] = {ga.x, ga.y, ga.z, ga.w, gb.x, gb.y, gb.z, gb.w}, lb[8] = {ba.x, ba.y, ba.z, ba.w, bb.x, bb.y, bb.z, bb.w};
; #pragma unroll
;                 for (int e = 0; e < 8; ++e) { const unsigned wa = rawA[it][e >> 1], wb = rawB[it][e >> 1]; const float xa = (e & 1) ? bfhi(wa) : bflo(wa), xb = (e & 1) ? bfhi(wb) : bflo(wb);
;                     const float ya = (xa - meanA) * rstdA * lg[e] + lb[e], yb = (xb - meanB) * rstdB * lg[e] + lb[e];
;                     *(LAS unsigned*)(Vt + (c0 + e) * LST + 4 * lane) = pk2(ya, yb); } } }
;         __syncthreads();
	v_sub_f32_e32 v73, v73, v96
	v_mul_f32_e32 v73, v97, v73
	v_sub_f32_e32 v74, v74, v98
	v_fma_f32 v73, v73, v89, v105
	v_mul_f32_e32 v74, v99, v74
	v_fma_f32 v74, v74, v89, v105
	v_bfe_u32 v76, v73, 16, 1
	v_add3_u32 v73, v73, v76, s37
	v_bfe_u32 v76, v74, 16, 1
	v_lshrrev_b32_e32 v73, 16, v73
	v_add3_u32 v74, v74, v76, s37
	v_and_or_b32 v73, v74, s68, v73
	v_add_u32_e32 v74, 0x9c00, v128
	ds_write2_b32 v74, v72, v73 offset0:80 offset1:148
	v_lshlrev_b32_e32 v72, 16, v75
	v_lshlrev_b32_e32 v73, 16, v79
	v_sub_f32_e32 v72, v72, v96
	v_mul_f32_e32 v72, v97, v72
	v_sub_f32_e32 v73, v73, v98
	v_fma_f32 v72, v72, v90, v106
	v_mul_f32_e32 v73, v99, v73
	v_fma_f32 v73, v73, v90, v106
	v_bfe_u32 v74, v72, 16, 1
	v_add3_u32 v72, v72, v74, s37
	v_bfe_u32 v74, v73, 16, 1
	v_lshrrev_b32_e32 v72, 16, v72
	v_add3_u32 v73, v73, v74, s37
	v_and_or_b32 v72, v73, s68, v72
	v_and_b32_e32 v73, 0xffff0000, v75
	v_and_b32_e32 v74, 0xffff0000, v79
	v_sub_f32_e32 v73, v73, v96
	v_mul_f32_e32 v73, v97, v73
	v_sub_f32_e32 v74, v74, v98
	v_fma_f32 v73, v73, v91, v107
	v_mul_f32_e32 v74, v99, v74
	v_fmac_f32_e32 v107, v74, v91
	v_bfe_u32 v74, v73, 16, 1
	v_add3_u32 v73, v73, v74, s37
	v_bfe_u32 v74, v107, 16, 1
	v_lshrrev_b32_e32 v73, 16, v73
	v_add3_u32 v74, v107, v74, s37
	v_and_or_b32 v73, v74, s68, v73
	v_add_u32_e32 v74, 0x9e00, v128
	ds_write2_b32 v74, v72, v73 offset0:88 offset1:156
	v_lshlrev_b32_e32 v72, 16, v68
	v_lshlrev_b32_e32 v73, 16, v64
	v_sub_f32_e32 v72, v72, v96
	v_mul_f32_e32 v72, v97, v72
	v_sub_f32_e32 v73, v73, v98
	v_fma_f32 v72, v72, v84, v100
	v_mul_f32_e32 v73, v99, v73
	v_fma_f32 v73, v73, v84, v100
	v_bfe_u32 v74, v72, 16, 1
	v_and_b32_e32 v68, 0xffff0000, v68
	v_add3_u32 v72, v72, v74, s37
	v_bfe_u32 v74, v73, 16, 1
	v_and_b32_e32 v64, 0xffff0000, v64
	v_sub_f32_e32 v68, v68, v96
	v_lshrrev_b32_e32 v72, 16, v72
	v_add3_u32 v73, v73, v74, s37
	v_mul_f32_e32 v68, v97, v68
	v_sub_f32_e32 v64, v64, v98
	v_and_or_b32 v72, v73, s68, v72
	v_fma_f32 v68, v68, v85, v101
	v_mul_f32_e32 v64, v99, v64
	ds_write_b32 v120, v72 offset:39168
	v_fma_f32 v64, v64, v85, v101
	v_bfe_u32 v72, v68, 16, 1
	v_add3_u32 v68, v68, v72, s37
	v_bfe_u32 v72, v64, 16, 1
	v_lshrrev_b32_e32 v68, 16, v68
	v_add3_u32 v64, v64, v72, s37
	v_and_or_b32 v64, v64, s68, v68
	v_lshlrev_b32_e32 v68, 16, v69
	v_lshlrev_b32_e32 v72, 16, v65
	v_sub_f32_e32 v68, v68, v96
	v_mul_f32_e32 v68, v97, v68
	v_sub_f32_e32 v72, v72, v98
	v_fma_f32 v68, v68, v86, v102
	v_mul_f32_e32 v72, v99, v72
	v_fma_f32 v72, v72, v86, v102
	v_bfe_u32 v73, v68, 16, 1
	v_add3_u32 v68, v68, v73, s37
	v_bfe_u32 v73, v72, 16, 1
	v_lshrrev_b32_e32 v68, 16, v68
	v_add3_u32 v72, v72, v73, s37
	v_and_or_b32 v68, v72, s68, v68
	v_add_u32_e32 v72, 0xa000, v128
	ds_write2_b32 v72, v64, v68 offset0:164 offset1:232
	v_and_b32_e32 v64, 0xffff0000, v69
	v_and_b32_e32 v65, 0xffff0000, v65
	v_sub_f32_e32 v64, v64, v96
	v_mul_f32_e32 v64, v97, v64
	v_sub_f32_e32 v65, v65, v98
	v_fma_f32 v64, v64, v87, v103
	v_mul_f32_e32 v65, v99, v65
	v_fmac_f32_e32 v103, v65, v87
	v_bfe_u32 v65, v64, 16, 1
	v_add3_u32 v64, v64, v65, s37
	v_bfe_u32 v65, v103, 16, 1
	v_lshrrev_b32_e32 v64, 16, v64
	v_add3_u32 v65, v103, v65, s37
	v_and_or_b32 v64, v65, s68, v64
	v_lshlrev_b32_e32 v65, 16, v70
	v_lshlrev_b32_e32 v68, 16, v66
	v_sub_f32_e32 v65, v65, v96
	v_mul_f32_e32 v65, v97, v65
	v_sub_f32_e32 v68, v68, v98
	v_fma_f32 v65, v65, v80, v92
	v_mul_f32_e32 v68, v99, v68
	v_fma_f32 v68, v68, v80, v92
	v_bfe_u32 v69, v65, 16, 1
	v_add3_u32 v65, v65, v69, s37
	v_bfe_u32 v69, v68, 16, 1
	v_lshrrev_b32_e32 v65, 16, v65
	v_add3_u32 v68, v68, v69, s37
	v_and_or_b32 v65, v68, s68, v65
	v_add_u32_e32 v68, 0xa400, v128
	ds_write2_b32 v68, v64, v65 offset0:44 offset1:112
	v_and_b32_e32 v64, 0xffff0000, v70
	v_and_b32_e32 v65, 0xffff0000, v66
	v_sub_f32_e32 v64, v64, v96
	v_mul_f32_e32 v64, v97, v64
	v_sub_f32_e32 v65, v65, v98
	v_fma_f32 v64, v64, v81, v93
	v_mul_f32_e32 v65, v99, v65
	v_fma_f32 v65, v65, v81, v93
	v_bfe_u32 v66, v64, 16, 1
	v_add3_u32 v64, v64, v66, s37
	v_bfe_u32 v66, v65, 16, 1
	v_lshrrev_b32_e32 v64, 16, v64
	v_add3_u32 v65, v65, v66, s37
	v_and_or_b32 v64, v65, s68, v64
	v_lshlrev_b32_e32 v65, 16, v71
	v_lshlrev_b32_e32 v66, 16, v67
	v_sub_f32_e32 v65, v65, v96
	v_mul_f32_e32 v65, v97, v65
	v_sub_f32_e32 v66, v66, v98
	v_fma_f32 v65, v65, v82, v94
	v_mul_f32_e32 v66, v99, v66
	v_fma_f32 v66, v66, v82, v94
	v_bfe_u32 v69, v65, 16, 1
	v_add3_u32 v65, v65, v69, s37
	v_bfe_u32 v69, v66, 16, 1
	v_lshrrev_b32_e32 v65, 16, v65
	v_add3_u32 v66, v66, v69, s37
	v_and_or_b32 v65, v66, s68, v65
	ds_write2_b32 v68, v64, v65 offset0:180 offset1:248
	v_and_b32_e32 v64, 0xffff0000, v71
	v_and_b32_e32 v65, 0xffff0000, v67
	v_sub_f32_e32 v64, v64, v96
	v_mul_f32_e32 v64, v97, v64
	v_sub_f32_e32 v65, v65, v98
	v_fma_f32 v64, v64, v83, v95
	v_mul_f32_e32 v65, v99, v65
	v_fmac_f32_e32 v95, v65, v83
	v_bfe_u32 v65, v64, 16, 1
	v_add3_u32 v64, v64, v65, s37
	v_bfe_u32 v65, v95, 16, 1
	v_lshrrev_b32_e32 v64, 16, v64
	v_add3_u32 v65, v95, v65, s37
	v_and_or_b32 v64, v65, s68, v64
	ds_write_b32 v128, v64 offset:43248
	s_waitcnt lgkmcnt(0)
	s_barrier
; #define LAS __attribute__((address_space(3)))
; __device__ __forceinline__ void spatial_phase(const Frame& F, bf16* Z, const float* stats, const float* lng, const float* lnb, const float* ws, const float* bs, bool do_store = true) {
;     ...
;         f32x4 acc[8][2];
; #pragma unroll
;         for (int m = 0; m < 8; ++m) { acc[m][0] = (f32x4){0.f, 0.f, 0.f, 0.f}; acc[m][1] = (f32x4){0.f, 0.f, 0.f, 0.f}; }
; #pragma unroll
;         for (int ks = 0; ks < 4; ++ks) { bf16x8 Bf[2];
; #pragma unroll
;             for (int n = 0; n < 2; ++n) Bf[n] = *(const LAS bf16x8*)(Vt + (32 * w + 16 * n + fr) * LST + (ks * 32 + fq * 8) * 2);
; #pragma unroll
;             for (int m = 0; m < 8; ++m) if (32 * ks <= 16 * m + 15) { const bf16x8 Af = *(const LAS bf16x8*)(Wl + (16 * m + fr) * LST + (ks * 32 + fq * 8) * 2);
; #pragma unroll
;                 for (int n = 0; n < 2; ++n) acc[m][n] = __builtin_amdgcn_mfma_f32_16x16x32_bf16(Bf[n], Af, acc[m][n], 0, 0, 0); } }
; #pragma unroll
;         for (int m = 0; m < 8; ++m) { const int t = 16 * m + fr; const float b = bs[g * 128 + t];
	v_lshlrev_b32_e32 v8, 2, v132
	v_lshl_or_b32 v8, s45, 9, v8
	global_load_dword v0, v8, s[22:23]
	global_load_dword v1, v8, s[22:23] offset:64
	global_load_dword v2, v8, s[22:23] offset:128
	global_load_dword v3, v8, s[22:23] offset:192
	global_load_dword v4, v8, s[22:23] offset:256
	global_load_dword v5, v8, s[22:23] offset:320
	global_load_dword v6, v8, s[22:23] offset:384
	global_load_dword v7, v8, s[22:23] offset:448
	ds_read_b128 v[64:67], v201 offset:34816
	ds_read_b128 v[68:71], v201 offset:39168
	ds_read_b128 v[72:75], v222
	ds_read_b128 v[96:99], v222 offset:21760
	s_waitcnt lgkmcnt(1)
	v_mfma_f32_16x16x32_bf16 v[128:131], v[64:67], v[72:75], 0
	ds_read_b128 v[80:83], v222 offset:13056
	ds_read_b128 v[88:91], v222 offset:17408
	v_mfma_f32_16x16x32_bf16 v[124:127], v[68:71], v[72:75], 0
	ds_read_b128 v[72:75], v222 offset:4352
	s_waitcnt lgkmcnt(3)
	v_mfma_f32_16x16x32_bf16 v[224:227], v[64:67], v[96:99], 0
	v_mfma_f32_16x16x32_bf16 v[238:241], v[68:71], v[96:99], 0
	ds_read_b128 v[96:99], v222 offset:26112
	s_waitcnt lgkmcnt(1)
	v_mfma_f32_16x16x32_bf16 v[108:111], v[64:67], v[72:75], 0
	v_mfma_f32_16x16x32_bf16 v[104:107], v[68:71], v[72:75], 0
	ds_read_b128 v[72:75], v222 offset:8704
	s_waitcnt lgkmcnt(1)
	v_mfma_f32_16x16x32_bf16 v[242:245], v[64:67], v[96:99], 0
	v_mfma_f32_16x16x32_bf16 v[246:249], v[68:71], v[96:99], 0
	ds_read_b128 v[96:99], v222 offset:30464
	s_waitcnt lgkmcnt(1)
	v_mfma_f32_16x16x32_bf16 v[76:79], v[64:67], v[72:75], 0
	v_mfma_f32_16x16x32_bf16 v[72:75], v[68:71], v[72:75], 0
	v_mfma_f32_16x16x32_bf16 v[84:87], v[64:67], v[80:83], 0
	v_mfma_f32_16x16x32_bf16 v[80:83], v[68:71], v[80:83], 0
	v_mfma_f32_16x16x32_bf16 v[92:95], v[64:67], v[88:91], 0
	v_mfma_f32_16x16x32_bf16 v[88:91], v[68:71], v[88:91], 0
	s_waitcnt lgkmcnt(0)
	v_mfma_f32_16x16x32_bf16 v[64:67], v[64:67], v[96:99], 0
	v_mfma_f32_16x16x32_bf16 v[68:71], v[68:71], v[96:99], 0
	ds_read_b128 v[138:141], v201 offset:34880
	ds_read_b128 v[142:145], v201 offset:39232
	ds_read_b128 v[96:99], v222 offset:8768
	s_waitcnt lgkmcnt(0)
	v_mfma_f32_16x16x32_bf16 v[116:119], v[142:145], v[96:99], v[72:75]
	s_nop 2
	ds_read_b128 v[72:75], v222 offset:13120
	v_mfma_f32_16x16x32_bf16 v[120:123], v[138:141], v[96:99], v[76:79]
	s_waitcnt lgkmcnt(0)
	v_mfma_f32_16x16x32_bf16 v[100:103], v[138:141], v[72:75], v[84:87]
	v_mfma_f32_16x16x32_bf16 v[96:99], v[142:145], v[72:75], v[80:83]
	ds_read_b128 v[72:75], v222 offset:17472
	s_nop 1
	ds_read_b128 v[80:83], v222 offset:21824
	s_waitcnt lgkmcnt(1)
	v_mfma_f32_16x16x32_bf16 v[76:79], v[138:141], v[72:75], v[92:95]
	v_mfma_f32_16x16x32_bf16 v[72:75], v[142:145], v[72:75], v[88:91]
	s_nop 2
	ds_read_b128 v[88:91], v222 offset:26176
	s_waitcnt lgkmcnt(1)
	v_mfma_f32_16x16x32_bf16 v[84:87], v[138:141], v[80:83], v[224:227]
	v_mfma_f32_16x16x32_bf16 v[80:83], v[142:145], v[80:83], v[238:241]
	s_waitcnt lgkmcnt(0)
	v_mfma_f32_16x16x32_bf16 v[224:227], v[138:141], v[88:91], v[242:245]
	v_mfma_f32_16x16x32_bf16 v[238:241], v[142:145], v[88:91], v[246:249]
	ds_read_b128 v[88:91], v222 offset:30528
	s_waitcnt lgkmcnt(0)
	v_mfma_f32_16x16x32_bf16 v[64:67], v[138:141], v[88:91], v[64:67]
	v_mfma_f32_16x16x32_bf16 v[68:71], v[142:145], v[88:91], v[68:71]
	ds_read_b128 v[138:141], v201 offset:34944
	ds_read_b128 v[142:145], v201 offset:39296
	ds_read_b128 v[88:91], v222 offset:17536
	s_waitcnt lgkmcnt(0)
	v_mfma_f32_16x16x32_bf16 v[92:95], v[138:141], v[88:91], v[76:79]
	v_mfma_f32_16x16x32_bf16 v[88:91], v[142:145], v[88:91], v[72:75]
	s_nop 2
	ds_read_b128 v[72:75], v222 offset:21888
	s_waitcnt lgkmcnt(0)
	v_mfma_f32_16x16x32_bf16 v[84:87], v[138:141], v[72:75], v[84:87]
	v_mfma_f32_16x16x32_bf16 v[80:83], v[142:145], v[72:75], v[80:83]
	ds_read_b128 v[72:75], v222 offset:26240
	s_waitcnt lgkmcnt(0)
	v_mfma_f32_16x16x32_bf16 v[76:79], v[138:141], v[72:75], v[224:227]
	s_nop 2
	ds_read_b128 v[224:227], v222 offset:30592
	v_mfma_f32_16x16x32_bf16 v[72:75], v[142:145], v[72:75], v[238:241]
	s_waitcnt lgkmcnt(0)
	v_mfma_f32_16x16x32_bf16 v[64:67], v[138:141], v[224:227], v[64:67]
	v_mfma_f32_16x16x32_bf16 v[138:141], v[142:145], v[224:227], v[68:71]
	s_nop 2
	ds_read_b128 v[68:71], v201 offset:35008
	ds_read_b128 v[142:145], v201 offset:39360
	ds_read_b128 v[224:227], v222 offset:26304
	s_waitcnt lgkmcnt(0)
	v_mfma_f32_16x16x32_bf16 v[76:79], v[68:71], v[224:227], v[76:79]
	v_mfma_f32_16x16x32_bf16 v[72:75], v[142:145], v[224:227], v[72:75]
	ds_read_b128 v[224:227], v222 offset:30656
	s_waitcnt lgkmcnt(0)
	v_mfma_f32_16x16x32_bf16 v[68:71], v[68:71], v[224:227], v[64:67]
	v_mfma_f32_16x16x32_bf16 v[64:67], v[142:145], v[224:227], v[138:141]
	s_cbranch_vccnz .LBB0_716
; __device__ __forceinline__ unsigned pk2(float lo, float hi) { return f2bf(lo) | (f2bf(hi) << 16); }
; __device__ __forceinline__ float bflo(unsigned w) { return __uint_as_float(w << 16); }
; __device__ __forceinline__ float bfhi(unsigned w) { return __uint_as_float(w & 0xffff0000u); }
; __device__ __forceinline__ void spatial_phase(const Frame& F, bf16* Z, const float* stats, const float* lng, const float* lnb, const float* ws, const float* bs, bool do_store = true) {
;     ...
;         for (int m = 0; m < 8; ++m) { const int t = 16 * m + fr; const float b = bs[g * 128 + t];
; #pragma unroll
;             for (int n = 0; n < 2; ++n) { const int c = 32 * w + 16 * n + 4 * fq; v2u* p = (v2u*)(Z + (row0 + t) * 4096 + 256 * g + c); const v2u u2 = uu[m][n];
;                 const float o0 = bflo(u2.x) * (acc[m][n][0] + b), o1 = bfhi(u2.x) * (acc[m][n][1] + b), o2 = bflo(u2.y) * (acc[m][n][2] + b), o3 = bfhi(u2.y) * (acc[m][n][3] + b);
;                 if (do_store) *p = (v2u){pk2(o0, o1), pk2(o2, o3)}; } }
	s_nop 1
	s_lshl_b32 s12, s12, 1
	v_mov_b32_e32 v144, v129
	v_mov_b32_e32 v145, v131
	s_add_u32 s12, s26, s12
	v_and_b32_e32 v141, 0xffff0000, v221
	v_and_b32_e32 v140, 0xffff0000, v220
	v_lshlrev_b32_e32 v143, 16, v221
	v_lshlrev_b32_e32 v142, 16, v220
	v_mov_b32_e32 v129, v130
	v_mov_b32_e32 v220, v125
	v_mov_b32_e32 v221, v127
	v_mov_b32_e32 v125, v126
	s_addc_u32 s13, s27, 0
	v_and_b32_e32 v131, 0xffff0000, v219
	v_and_b32_e32 v130, 0xffff0000, v218
	v_lshlrev_b32_e32 v219, 16, v219
	v_lshlrev_b32_e32 v218, 16, v218
	v_lshl_add_u64 v[126:127], s[12:13], 0, v[216:217]
	v_lshl_add_u64 v[126:127], v[126:127], 0, v[164:165]
	s_waitcnt vmcnt(0)
	v_mov_b32_e32 v138, v0
	v_pk_add_f32 v[144:145], v[144:145], v[138:139] op_sel_hi:[1,0]
	v_pk_add_f32 v[128:129], v[128:129], v[138:139] op_sel_hi:[1,0]
	v_pk_add_f32 v[216:217], v[220:221], v[138:139] op_sel_hi:[1,0]
	v_pk_add_f32 v[124:125], v[124:125], v[138:139] op_sel_hi:[1,0]
	v_pk_mul_f32 v[138:139], v[144:145], v[140:141]
	v_pk_mul_f32 v[128:129], v[128:129], v[142:143]
	v_pk_mul_f32 v[130:131], v[216:217], v[130:131]
	v_pk_mul_f32 v[124:125], v[124:125], v[218:219]
	v_and_b32_sdwa v142, v139, v233 dst_sel:DWORD dst_unused:UNUSED_PAD src0_sel:WORD_1 src1_sel:DWORD
	v_and_b32_sdwa v143, v138, v233 dst_sel:DWORD dst_unused:UNUSED_PAD src0_sel:WORD_1 src1_sel:DWORD
	v_and_b32_sdwa v140, v129, v233 dst_sel:DWORD dst_unused:UNUSED_PAD src0_sel:WORD_1 src1_sel:DWORD
	v_and_b32_sdwa v141, v128, v233 dst_sel:DWORD dst_unused:UNUSED_PAD src0_sel:WORD_1 src1_sel:DWORD
	v_and_b32_sdwa v144, v125, v233 dst_sel:DWORD dst_unused:UNUSED_PAD src0_sel:WORD_1 src1_sel:DWORD
	v_and_b32_sdwa v145, v124, v233 dst_sel:DWORD dst_unused:UNUSED_PAD src0_sel:WORD_1 src1_sel:DWORD
	v_and_b32_sdwa v216, v131, v233 dst_sel:DWORD dst_unused:UNUSED_PAD src0_sel:WORD_1 src1_sel:DWORD
	v_and_b32_sdwa v217, v130, v233 dst_sel:DWORD dst_unused:UNUSED_PAD src0_sel:WORD_1 src1_sel:DWORD
	v_add3_u32 v139, v139, v142, s37
	v_add3_u32 v138, v138, v143, s37
	v_add3_u32 v128, v128, v141, s37
	v_add3_u32 v129, v129, v140, s37
	v_add3_u32 v140, v124, v145, s37
	v_add3_u32 v141, v125, v144, s37
	v_add3_u32 v124, v131, v216, s37
	v_add3_u32 v125, v130, v217, s37
	v_and_b32_e32 v130, 0xffff0000, v139
	v_and_b32_e32 v131, 0xffff0000, v138
	v_and_b32_e32 v138, 0xffff0000, v124
	v_and_b32_e32 v139, 0xffff0000, v125
	v_or_b32_sdwa v125, v130, v129 dst_sel:DWORD dst_unused:UNUSED_PAD src0_sel:DWORD src1_sel:WORD_1
	v_or_b32_sdwa v124, v131, v128 dst_sel:DWORD dst_unused:UNUSED_PAD src0_sel:DWORD src1_sel:WORD_1
	v_or_b32_sdwa v129, v138, v141 dst_sel:DWORD dst_unused:UNUSED_PAD src0_sel:DWORD src1_sel:WORD_1
	v_or_b32_sdwa v128, v139, v140 dst_sel:DWORD dst_unused:UNUSED_PAD src0_sel:DWORD src1_sel:WORD_1
	global_store_dwordx2 v[126:127], v[124:125], off
	global_store_dwordx2 v[126:127], v[128:129], off offset:32
	v_mov_b32_e32 v124, v1
	v_mov_b32_e32 v130, v109
	v_mov_b32_e32 v131, v111
	v_and_b32_e32 v127, 0xffff0000, v215
	v_and_b32_e32 v126, 0xffff0000, v214
	v_mov_b32_e32 v109, v110
	v_mov_b32_e32 v140, v105
	v_mov_b32_e32 v141, v107
	v_mov_b32_e32 v105, v106
	v_lshlrev_b32_e32 v129, 16, v215
	v_lshlrev_b32_e32 v128, 16, v214
	v_and_b32_e32 v111, 0xffff0000, v213
	v_and_b32_e32 v110, 0xffff0000, v212
	v_lshlrev_b32_e32 v139, 16, v213
	v_lshlrev_b32_e32 v138, 16, v212
	v_lshl_add_u64 v[106:107], s[12:13], 0, v[210:211]
	v_lshl_add_u64 v[106:107], v[106:107], 0, v[164:165]
	v_pk_add_f32 v[130:131], v[130:131], v[124:125] op_sel_hi:[1,0]
	v_pk_add_f32 v[108:109], v[108:109], v[124:125] op_sel_hi:[1,0]
	v_pk_add_f32 v[140:141], v[140:141], v[124:125] op_sel_hi:[1,0]
	v_pk_add_f32 v[104:105], v[104:105], v[124:125] op_sel_hi:[1,0]
	v_pk_mul_f32 v[124:125], v[130:131], v[126:127]
	v_pk_mul_f32 v[108:109], v[108:109], v[128:129]
	v_pk_mul_f32 v[110:111], v[140:141], v[110:111]
	v_pk_mul_f32 v[104:105], v[104:105], v[138:139]
	v_and_b32_sdwa v128, v125, v233 dst_sel:DWORD dst_unused:UNUSED_PAD src0_sel:WORD_1 src1_sel:DWORD
	v_and_b32_sdwa v129, v124, v233 dst_sel:DWORD dst_unused:UNUSED_PAD src0_sel:WORD_1 src1_sel:DWORD
	v_and_b32_sdwa v126, v109, v233 dst_sel:DWORD dst_unused:UNUSED_PAD src0_sel:WORD_1 src1_sel:DWORD
	v_and_b32_sdwa v127, v108, v233 dst_sel:DWORD dst_unused:UNUSED_PAD src0_sel:WORD_1 src1_sel:DWORD
	v_and_b32_sdwa v130, v105, v233 dst_sel:DWORD dst_unused:UNUSED_PAD src0_sel:WORD_1 src1_sel:DWORD
	v_and_b32_sdwa v131, v104, v233 dst_sel:DWORD dst_unused:UNUSED_PAD src0_sel:WORD_1 src1_sel:DWORD
	v_and_b32_sdwa v138, v111, v233 dst_sel:DWORD dst_unused:UNUSED_PAD src0_sel:WORD_1 src1_sel:DWORD
	v_and_b32_sdwa v139, v110, v233 dst_sel:DWORD dst_unused:UNUSED_PAD src0_sel:WORD_1 src1_sel:DWORD
	v_add3_u32 v125, v125, v128, s37
	v_add3_u32 v124, v124, v129, s37
	v_add3_u32 v108, v108, v127, s37
	v_add3_u32 v109, v109, v126, s37
	v_add3_u32 v126, v104, v131, s37
	v_add3_u32 v127, v105, v130, s37
	v_add3_u32 v104, v111, v138, s37
	v_add3_u32 v105, v110, v139, s37
	v_and_b32_e32 v110, 0xffff0000, v125
	v_and_b32_e32 v111, 0xffff0000, v124
	v_and_b32_e32 v124, 0xffff0000, v104
	v_and_b32_e32 v125, 0xffff0000, v105
	v_or_b32_sdwa v105, v110, v109 dst_sel:DWORD dst_unused:UNUSED_PAD src0_sel:DWORD src1_sel:WORD_1
	v_or_b32_sdwa v104, v111, v108 dst_sel:DWORD dst_unused:UNUSED_PAD src0_sel:DWORD src1_sel:WORD_1
	v_or_b32_sdwa v109, v124, v127 dst_sel:DWORD dst_unused:UNUSED_PAD src0_sel:DWORD src1_sel:WORD_1
	v_or_b32_sdwa v108, v125, v126 dst_sel:DWORD dst_unused:UNUSED_PAD src0_sel:DWORD src1_sel:WORD_1
	global_store_dwordx2 v[106:107], v[104:105], off
	global_store_dwordx2 v[106:107], v[108:109], off offset:32
	v_mov_b32_e32 v104, v2
; __device__ __forceinline__ unsigned pk2(float lo, float hi) { return f2bf(lo) | (f2bf(hi) << 16); }
; __device__ __forceinline__ float bflo(unsigned w) { return __uint_as_float(w << 16); }
; __device__ __forceinline__ float bfhi(unsigned w) { return __uint_as_float(w & 0xffff0000u); }
; __device__ __forceinline__ void spatial_phase(const Frame& F, bf16* Z, const float* stats, const float* lng, const float* lnb, const float* ws, const float* bs, bool do_store = true) {
;     ...
;         for (int m = 0; m < 8; ++m) { const int t = 16 * m + fr; const float b = bs[g * 128 + t];
; #pragma unroll
;             for (int n = 0; n < 2; ++n) { const int c = 32 * w + 16 * n + 4 * fq; v2u* p = (v2u*)(Z + (row0 + t) * 4096 + 256 * g + c); const v2u u2 = uu[m][n];
;                 const float o0 = bflo(u2.x) * (acc[m][n][0] + b), o1 = bfhi(u2.x) * (acc[m][n][1] + b), o2 = bflo(u2.y) * (acc[m][n][2] + b), o3 = bfhi(u2.y) * (acc[m][n][3] + b);
;                 if (do_store) *p = (v2u){pk2(o0, o1), pk2(o2, o3)}; } }
	v_mov_b32_e32 v110, v121
	v_mov_b32_e32 v111, v123
	v_and_b32_e32 v107, 0xffff0000, v209
	v_and_b32_e32 v106, 0xffff0000, v208
	v_mov_b32_e32 v121, v122
	v_mov_b32_e32 v126, v117
	v_mov_b32_e32 v127, v119
	v_mov_b32_e32 v117, v118
	v_lshlrev_b32_e32 v109, 16, v209
	v_lshlrev_b32_e32 v108, 16, v208
	v_and_b32_e32 v123, 0xffff0000, v207
	v_and_b32_e32 v122, 0xffff0000, v206
	v_lshlrev_b32_e32 v125, 16, v207
	v_lshlrev_b32_e32 v124, 16, v206
	v_lshl_add_u64 v[118:119], s[12:13], 0, v[204:205]
	v_lshl_add_u64 v[118:119], v[118:119], 0, v[164:165]
	v_pk_add_f32 v[110:111], v[110:111], v[104:105] op_sel_hi:[1,0]
	v_pk_add_f32 v[120:121], v[120:121], v[104:105] op_sel_hi:[1,0]
	v_pk_add_f32 v[126:127], v[126:127], v[104:105] op_sel_hi:[1,0]
	v_pk_add_f32 v[104:105], v[116:117], v[104:105] op_sel_hi:[1,0]
	v_pk_mul_f32 v[106:107], v[110:111], v[106:107]
	v_pk_mul_f32 v[108:109], v[120:121], v[108:109]
	v_pk_mul_f32 v[110:111], v[126:127], v[122:123]
	v_pk_mul_f32 v[104:105], v[104:105], v[124:125]
	v_and_b32_sdwa v120, v107, v233 dst_sel:DWORD dst_unused:UNUSED_PAD src0_sel:WORD_1 src1_sel:DWORD
	v_and_b32_sdwa v121, v106, v233 dst_sel:DWORD dst_unused:UNUSED_PAD src0_sel:WORD_1 src1_sel:DWORD
	v_and_b32_sdwa v116, v109, v233 dst_sel:DWORD dst_unused:UNUSED_PAD src0_sel:WORD_1 src1_sel:DWORD
	v_and_b32_sdwa v117, v108, v233 dst_sel:DWORD dst_unused:UNUSED_PAD src0_sel:WORD_1 src1_sel:DWORD
	v_and_b32_sdwa v122, v105, v233 dst_sel:DWORD dst_unused:UNUSED_PAD src0_sel:WORD_1 src1_sel:DWORD
	v_and_b32_sdwa v123, v104, v233 dst_sel:DWORD dst_unused:UNUSED_PAD src0_sel:WORD_1 src1_sel:DWORD
	v_and_b32_sdwa v124, v111, v233 dst_sel:DWORD dst_unused:UNUSED_PAD src0_sel:WORD_1 src1_sel:DWORD
	v_and_b32_sdwa v125, v110, v233 dst_sel:DWORD dst_unused:UNUSED_PAD src0_sel:WORD_1 src1_sel:DWORD
	v_add3_u32 v107, v107, v120, s37
	v_add3_u32 v106, v106, v121, s37
	v_add3_u32 v108, v108, v117, s37
	v_add3_u32 v109, v109, v116, s37
	v_add3_u32 v116, v104, v123, s37
	v_add3_u32 v117, v105, v122, s37
	v_add3_u32 v104, v111, v124, s37
	v_add3_u32 v105, v110, v125, s37
	v_and_b32_e32 v107, 0xffff0000, v107
	v_and_b32_e32 v106, 0xffff0000, v106
	v_and_b32_e32 v110, 0xffff0000, v104
	v_and_b32_e32 v111, 0xffff0000, v105
	v_or_b32_sdwa v105, v107, v109 dst_sel:DWORD dst_unused:UNUSED_PAD src0_sel:DWORD src1_sel:WORD_1
	v_or_b32_sdwa v104, v106, v108 dst_sel:DWORD dst_unused:UNUSED_PAD src0_sel:DWORD src1_sel:WORD_1
	v_or_b32_sdwa v107, v110, v117 dst_sel:DWORD dst_unused:UNUSED_PAD src0_sel:DWORD src1_sel:WORD_1
	v_or_b32_sdwa v106, v111, v116 dst_sel:DWORD dst_unused:UNUSED_PAD src0_sel:DWORD src1_sel:WORD_1
	global_store_dwordx2 v[118:119], v[104:105], off
	global_store_dwordx2 v[118:119], v[106:107], off offset:32
	v_mov_b32_e32 v104, v3
	v_mov_b32_e32 v110, v101
	v_mov_b32_e32 v111, v103
	v_and_b32_e32 v107, 0xffff0000, v195
	v_and_b32_e32 v106, 0xffff0000, v194
	v_mov_b32_e32 v101, v102
	v_mov_b32_e32 v118, v97
	v_mov_b32_e32 v119, v99
	v_mov_b32_e32 v97, v98
	v_lshlrev_b32_e32 v109, 16, v195
	v_lshlrev_b32_e32 v108, 16, v194
	v_and_b32_e32 v103, 0xffff0000, v193
	v_and_b32_e32 v102, 0xffff0000, v192
	v_lshlrev_b32_e32 v117, 16, v193
	v_lshlrev_b32_e32 v116, 16, v192
	v_lshl_add_u64 v[98:99], s[12:13], 0, v[190:191]
	v_lshl_add_u64 v[98:99], v[98:99], 0, v[164:165]
	v_pk_add_f32 v[110:111], v[110:111], v[104:105] op_sel_hi:[1,0]
	v_pk_add_f32 v[100:101], v[100:101], v[104:105] op_sel_hi:[1,0]
	v_pk_add_f32 v[118:119], v[118:119], v[104:105] op_sel_hi:[1,0]
	v_pk_add_f32 v[96:97], v[96:97], v[104:105] op_sel_hi:[1,0]
	v_pk_mul_f32 v[104:105], v[110:111], v[106:107]
	v_pk_mul_f32 v[100:101], v[100:101], v[108:109]
	v_pk_mul_f32 v[102:103], v[118:119], v[102:103]
	v_pk_mul_f32 v[96:97], v[96:97], v[116:117]
	v_and_b32_sdwa v108, v105, v233 dst_sel:DWORD dst_unused:UNUSED_PAD src0_sel:WORD_1 src1_sel:DWORD
	v_and_b32_sdwa v109, v104, v233 dst_sel:DWORD dst_unused:UNUSED_PAD src0_sel:WORD_1 src1_sel:DWORD
	v_and_b32_sdwa v106, v101, v233 dst_sel:DWORD dst_unused:UNUSED_PAD src0_sel:WORD_1 src1_sel:DWORD
	v_and_b32_sdwa v107, v100, v233 dst_sel:DWORD dst_unused:UNUSED_PAD src0_sel:WORD_1 src1_sel:DWORD
	v_and_b32_sdwa v110, v97, v233 dst_sel:DWORD dst_unused:UNUSED_PAD src0_sel:WORD_1 src1_sel:DWORD
	v_and_b32_sdwa v111, v96, v233 dst_sel:DWORD dst_unused:UNUSED_PAD src0_sel:WORD_1 src1_sel:DWORD
	v_and_b32_sdwa v116, v103, v233 dst_sel:DWORD dst_unused:UNUSED_PAD src0_sel:WORD_1 src1_sel:DWORD
	v_and_b32_sdwa v117, v102, v233 dst_sel:DWORD dst_unused:UNUSED_PAD src0_sel:WORD_1 src1_sel:DWORD
	v_add3_u32 v105, v105, v108, s37
	v_add3_u32 v104, v104, v109, s37
	v_add3_u32 v100, v100, v107, s37
	v_add3_u32 v101, v101, v106, s37
	v_add3_u32 v106, v96, v111, s37
	v_add3_u32 v107, v97, v110, s37
	v_add3_u32 v96, v103, v116, s37
	v_add3_u32 v97, v102, v117, s37
	v_and_b32_e32 v102, 0xffff0000, v105
	v_and_b32_e32 v103, 0xffff0000, v104
	v_and_b32_e32 v104, 0xffff0000, v96
	v_and_b32_e32 v105, 0xffff0000, v97
	v_or_b32_sdwa v97, v102, v101 dst_sel:DWORD dst_unused:UNUSED_PAD src0_sel:DWORD src1_sel:WORD_1
	v_or_b32_sdwa v96, v103, v100 dst_sel:DWORD dst_unused:UNUSED_PAD src0_sel:DWORD src1_sel:WORD_1
	v_or_b32_sdwa v101, v104, v107 dst_sel:DWORD dst_unused:UNUSED_PAD src0_sel:DWORD src1_sel:WORD_1
	v_or_b32_sdwa v100, v105, v106 dst_sel:DWORD dst_unused:UNUSED_PAD src0_sel:DWORD src1_sel:WORD_1
	global_store_dwordx2 v[98:99], v[96:97], off
	global_store_dwordx2 v[98:99], v[100:101], off offset:32
	v_mov_b32_e32 v96, v4
	v_mov_b32_e32 v102, v93
	v_mov_b32_e32 v103, v95
	v_and_b32_e32 v99, 0xffff0000, v189
	v_and_b32_e32 v98, 0xffff0000, v188
	v_mov_b32_e32 v93, v94
; __device__ __forceinline__ unsigned pk2(float lo, float hi) { return f2bf(lo) | (f2bf(hi) << 16); }
; __device__ __forceinline__ float bflo(unsigned w) { return __uint_as_float(w << 16); }
; __device__ __forceinline__ float bfhi(unsigned w) { return __uint_as_float(w & 0xffff0000u); }
; __device__ __forceinline__ void spatial_phase(const Frame& F, bf16* Z, const float* stats, const float* lng, const float* lnb, const float* ws, const float* bs, bool do_store = true) {
;     ...
;         for (int m = 0; m < 8; ++m) { const int t = 16 * m + fr; const float b = bs[g * 128 + t];
; #pragma unroll
;             for (int n = 0; n < 2; ++n) { const int c = 32 * w + 16 * n + 4 * fq; v2u* p = (v2u*)(Z + (row0 + t) * 4096 + 256 * g + c); const v2u u2 = uu[m][n];
;                 const float o0 = bflo(u2.x) * (acc[m][n][0] + b), o1 = bfhi(u2.x) * (acc[m][n][1] + b), o2 = bflo(u2.y) * (acc[m][n][2] + b), o3 = bfhi(u2.y) * (acc[m][n][3] + b);
;                 if (do_store) *p = (v2u){pk2(o0, o1), pk2(o2, o3)}; } }
	v_mov_b32_e32 v106, v89
	v_mov_b32_e32 v107, v91
	v_mov_b32_e32 v89, v90
	v_lshlrev_b32_e32 v101, 16, v189
	v_lshlrev_b32_e32 v100, 16, v188
	v_and_b32_e32 v95, 0xffff0000, v187
	v_and_b32_e32 v94, 0xffff0000, v186
	v_lshlrev_b32_e32 v105, 16, v187
	v_lshlrev_b32_e32 v104, 16, v186
	v_lshl_add_u64 v[90:91], s[12:13], 0, v[184:185]
	v_lshl_add_u64 v[90:91], v[90:91], 0, v[164:165]
	v_pk_add_f32 v[102:103], v[102:103], v[96:97] op_sel_hi:[1,0]
	v_pk_add_f32 v[92:93], v[92:93], v[96:97] op_sel_hi:[1,0]
	v_pk_add_f32 v[106:107], v[106:107], v[96:97] op_sel_hi:[1,0]
	v_pk_add_f32 v[88:89], v[88:89], v[96:97] op_sel_hi:[1,0]
	v_pk_mul_f32 v[96:97], v[102:103], v[98:99]
	v_pk_mul_f32 v[92:93], v[92:93], v[100:101]
	v_pk_mul_f32 v[94:95], v[106:107], v[94:95]
	v_pk_mul_f32 v[88:89], v[88:89], v[104:105]
	v_and_b32_sdwa v100, v97, v233 dst_sel:DWORD dst_unused:UNUSED_PAD src0_sel:WORD_1 src1_sel:DWORD
	v_and_b32_sdwa v101, v96, v233 dst_sel:DWORD dst_unused:UNUSED_PAD src0_sel:WORD_1 src1_sel:DWORD
	v_and_b32_sdwa v98, v93, v233 dst_sel:DWORD dst_unused:UNUSED_PAD src0_sel:WORD_1 src1_sel:DWORD
	v_and_b32_sdwa v99, v92, v233 dst_sel:DWORD dst_unused:UNUSED_PAD src0_sel:WORD_1 src1_sel:DWORD
	v_and_b32_sdwa v102, v89, v233 dst_sel:DWORD dst_unused:UNUSED_PAD src0_sel:WORD_1 src1_sel:DWORD
	v_and_b32_sdwa v103, v88, v233 dst_sel:DWORD dst_unused:UNUSED_PAD src0_sel:WORD_1 src1_sel:DWORD
	v_and_b32_sdwa v104, v95, v233 dst_sel:DWORD dst_unused:UNUSED_PAD src0_sel:WORD_1 src1_sel:DWORD
	v_and_b32_sdwa v105, v94, v233 dst_sel:DWORD dst_unused:UNUSED_PAD src0_sel:WORD_1 src1_sel:DWORD
	v_add3_u32 v97, v97, v100, s37
	v_add3_u32 v96, v96, v101, s37
	v_add3_u32 v92, v92, v99, s37
	v_add3_u32 v93, v93, v98, s37
	v_add3_u32 v98, v88, v103, s37
	v_add3_u32 v99, v89, v102, s37
	v_add3_u32 v88, v95, v104, s37
	v_add3_u32 v89, v94, v105, s37
	v_and_b32_e32 v94, 0xffff0000, v97
	v_and_b32_e32 v95, 0xffff0000, v96
	v_and_b32_e32 v96, 0xffff0000, v88
	v_and_b32_e32 v97, 0xffff0000, v89
	v_or_b32_sdwa v89, v94, v93 dst_sel:DWORD dst_unused:UNUSED_PAD src0_sel:DWORD src1_sel:WORD_1
	v_or_b32_sdwa v88, v95, v92 dst_sel:DWORD dst_unused:UNUSED_PAD src0_sel:DWORD src1_sel:WORD_1
	v_or_b32_sdwa v93, v96, v99 dst_sel:DWORD dst_unused:UNUSED_PAD src0_sel:DWORD src1_sel:WORD_1
	v_or_b32_sdwa v92, v97, v98 dst_sel:DWORD dst_unused:UNUSED_PAD src0_sel:DWORD src1_sel:WORD_1
	global_store_dwordx2 v[90:91], v[88:89], off
	global_store_dwordx2 v[90:91], v[92:93], off offset:32
	v_mov_b32_e32 v88, v5
	v_mov_b32_e32 v94, v85
	v_mov_b32_e32 v95, v87
	v_and_b32_e32 v91, 0xffff0000, v183
	v_and_b32_e32 v90, 0xffff0000, v182
	v_mov_b32_e32 v85, v86
	v_mov_b32_e32 v98, v81
	v_mov_b32_e32 v99, v83
	v_mov_b32_e32 v81, v82
	v_lshlrev_b32_e32 v93, 16, v183
	v_lshlrev_b32_e32 v92, 16, v182
	v_and_b32_e32 v87, 0xffff0000, v181
	v_and_b32_e32 v86, 0xffff0000, v180
	v_lshlrev_b32_e32 v97, 16, v181
	v_lshlrev_b32_e32 v96, 16, v180
	v_lshl_add_u64 v[82:83], s[12:13], 0, v[178:179]
	v_lshl_add_u64 v[82:83], v[82:83], 0, v[164:165]
	v_pk_add_f32 v[94:95], v[94:95], v[88:89] op_sel_hi:[1,0]
	v_pk_add_f32 v[84:85], v[84:85], v[88:89] op_sel_hi:[1,0]
	v_pk_add_f32 v[98:99], v[98:99], v[88:89] op_sel_hi:[1,0]
	v_pk_add_f32 v[80:81], v[80:81], v[88:89] op_sel_hi:[1,0]
	v_pk_mul_f32 v[88:89], v[94:95], v[90:91]
	v_pk_mul_f32 v[84:85], v[84:85], v[92:93]
	v_pk_mul_f32 v[86:87], v[98:99], v[86:87]
	v_pk_mul_f32 v[80:81], v[80:81], v[96:97]
	v_and_b32_sdwa v92, v89, v233 dst_sel:DWORD dst_unused:UNUSED_PAD src0_sel:WORD_1 src1_sel:DWORD
	v_and_b32_sdwa v93, v88, v233 dst_sel:DWORD dst_unused:UNUSED_PAD src0_sel:WORD_1 src1_sel:DWORD
	v_and_b32_sdwa v90, v85, v233 dst_sel:DWORD dst_unused:UNUSED_PAD src0_sel:WORD_1 src1_sel:DWORD
	v_and_b32_sdwa v91, v84, v233 dst_sel:DWORD dst_unused:UNUSED_PAD src0_sel:WORD_1 src1_sel:DWORD
	v_and_b32_sdwa v94, v81, v233 dst_sel:DWORD dst_unused:UNUSED_PAD src0_sel:WORD_1 src1_sel:DWORD
	v_and_b32_sdwa v95, v80, v233 dst_sel:DWORD dst_unused:UNUSED_PAD src0_sel:WORD_1 src1_sel:DWORD
	v_and_b32_sdwa v96, v87, v233 dst_sel:DWORD dst_unused:UNUSED_PAD src0_sel:WORD_1 src1_sel:DWORD
	v_and_b32_sdwa v97, v86, v233 dst_sel:DWORD dst_unused:UNUSED_PAD src0_sel:WORD_1 src1_sel:DWORD
	v_add3_u32 v89, v89, v92, s37
	v_add3_u32 v88, v88, v93, s37
	v_add3_u32 v84, v84, v91, s37
	v_add3_u32 v85, v85, v90, s37
	v_add3_u32 v90, v80, v95, s37
	v_add3_u32 v91, v81, v94, s37
	v_add3_u32 v80, v87, v96, s37
	v_add3_u32 v81, v86, v97, s37
	v_and_b32_e32 v86, 0xffff0000, v89
	v_and_b32_e32 v87, 0xffff0000, v88
	v_and_b32_e32 v88, 0xffff0000, v80
	v_and_b32_e32 v89, 0xffff0000, v81
	v_or_b32_sdwa v81, v86, v85 dst_sel:DWORD dst_unused:UNUSED_PAD src0_sel:DWORD src1_sel:WORD_1
	v_or_b32_sdwa v80, v87, v84 dst_sel:DWORD dst_unused:UNUSED_PAD src0_sel:DWORD src1_sel:WORD_1
	v_or_b32_sdwa v85, v88, v91 dst_sel:DWORD dst_unused:UNUSED_PAD src0_sel:DWORD src1_sel:WORD_1
	v_or_b32_sdwa v84, v89, v90 dst_sel:DWORD dst_unused:UNUSED_PAD src0_sel:DWORD src1_sel:WORD_1
	global_store_dwordx2 v[82:83], v[80:81], off
	global_store_dwordx2 v[82:83], v[84:85], off offset:32
	v_mov_b32_e32 v80, v6
	v_mov_b32_e32 v86, v77
	v_mov_b32_e32 v87, v79
; __device__ __forceinline__ unsigned pk2(float lo, float hi) { return f2bf(lo) | (f2bf(hi) << 16); }
; __device__ __forceinline__ float bflo(unsigned w) { return __uint_as_float(w << 16); }
; __device__ __forceinline__ float bfhi(unsigned w) { return __uint_as_float(w & 0xffff0000u); }
; __device__ __forceinline__ void spatial_phase(const Frame& F, bf16* Z, const float* stats, const float* lng, const float* lnb, const float* ws, const float* bs, bool do_store = true) {
;     ...
;         for (int m = 0; m < 8; ++m) { const int t = 16 * m + fr; const float b = bs[g * 128 + t];
; #pragma unroll
;             for (int n = 0; n < 2; ++n) { const int c = 32 * w + 16 * n + 4 * fq; v2u* p = (v2u*)(Z + (row0 + t) * 4096 + 256 * g + c); const v2u u2 = uu[m][n];
;                 const float o0 = bflo(u2.x) * (acc[m][n][0] + b), o1 = bfhi(u2.x) * (acc[m][n][1] + b), o2 = bflo(u2.y) * (acc[m][n][2] + b), o3 = bfhi(u2.y) * (acc[m][n][3] + b);
;                 if (do_store) *p = (v2u){pk2(o0, o1), pk2(o2, o3)}; } }
	v_and_b32_e32 v83, 0xffff0000, v177
	v_and_b32_e32 v82, 0xffff0000, v176
	v_mov_b32_e32 v77, v78
	v_mov_b32_e32 v90, v73
	v_mov_b32_e32 v91, v75
	v_mov_b32_e32 v73, v74
	v_lshlrev_b32_e32 v85, 16, v177
	v_lshlrev_b32_e32 v84, 16, v176
	v_and_b32_e32 v79, 0xffff0000, v175
	v_and_b32_e32 v78, 0xffff0000, v174
	v_lshlrev_b32_e32 v89, 16, v175
	v_lshlrev_b32_e32 v88, 16, v174
	v_lshl_add_u64 v[74:75], s[12:13], 0, v[172:173]
	v_lshl_add_u64 v[74:75], v[74:75], 0, v[164:165]
	v_pk_add_f32 v[86:87], v[86:87], v[80:81] op_sel_hi:[1,0]
	v_pk_add_f32 v[76:77], v[76:77], v[80:81] op_sel_hi:[1,0]
	v_pk_add_f32 v[90:91], v[90:91], v[80:81] op_sel_hi:[1,0]
	v_pk_add_f32 v[72:73], v[72:73], v[80:81] op_sel_hi:[1,0]
	v_pk_mul_f32 v[80:81], v[86:87], v[82:83]
	v_pk_mul_f32 v[76:77], v[76:77], v[84:85]
	v_pk_mul_f32 v[78:79], v[90:91], v[78:79]
	v_pk_mul_f32 v[72:73], v[72:73], v[88:89]
	v_and_b32_sdwa v84, v81, v233 dst_sel:DWORD dst_unused:UNUSED_PAD src0_sel:WORD_1 src1_sel:DWORD
	v_and_b32_sdwa v85, v80, v233 dst_sel:DWORD dst_unused:UNUSED_PAD src0_sel:WORD_1 src1_sel:DWORD
	v_and_b32_sdwa v82, v77, v233 dst_sel:DWORD dst_unused:UNUSED_PAD src0_sel:WORD_1 src1_sel:DWORD
	v_and_b32_sdwa v83, v76, v233 dst_sel:DWORD dst_unused:UNUSED_PAD src0_sel:WORD_1 src1_sel:DWORD
	v_and_b32_sdwa v86, v73, v233 dst_sel:DWORD dst_unused:UNUSED_PAD src0_sel:WORD_1 src1_sel:DWORD
	v_and_b32_sdwa v87, v72, v233 dst_sel:DWORD dst_unused:UNUSED_PAD src0_sel:WORD_1 src1_sel:DWORD
	v_and_b32_sdwa v88, v79, v233 dst_sel:DWORD dst_unused:UNUSED_PAD src0_sel:WORD_1 src1_sel:DWORD
	v_and_b32_sdwa v89, v78, v233 dst_sel:DWORD dst_unused:UNUSED_PAD src0_sel:WORD_1 src1_sel:DWORD
	v_add3_u32 v81, v81, v84, s37
	v_add3_u32 v80, v80, v85, s37
	v_add3_u32 v76, v76, v83, s37
	v_add3_u32 v77, v77, v82, s37
	v_add3_u32 v82, v72, v87, s37
	v_add3_u32 v83, v73, v86, s37
	v_add3_u32 v72, v79, v88, s37
	v_add3_u32 v73, v78, v89, s37
	v_and_b32_e32 v78, 0xffff0000, v81
	v_and_b32_e32 v79, 0xffff0000, v80
	v_and_b32_e32 v80, 0xffff0000, v72
	v_and_b32_e32 v81, 0xffff0000, v73
	v_or_b32_sdwa v73, v78, v77 dst_sel:DWORD dst_unused:UNUSED_PAD src0_sel:DWORD src1_sel:WORD_1
	v_or_b32_sdwa v72, v79, v76 dst_sel:DWORD dst_unused:UNUSED_PAD src0_sel:DWORD src1_sel:WORD_1
	v_or_b32_sdwa v77, v80, v83 dst_sel:DWORD dst_unused:UNUSED_PAD src0_sel:DWORD src1_sel:WORD_1
	v_or_b32_sdwa v76, v81, v82 dst_sel:DWORD dst_unused:UNUSED_PAD src0_sel:DWORD src1_sel:WORD_1
	global_store_dwordx2 v[74:75], v[72:73], off
	global_store_dwordx2 v[74:75], v[76:77], off offset:32
	v_mov_b32_e32 v72, v7
	v_mov_b32_e32 v78, v69
	v_mov_b32_e32 v79, v71
	v_and_b32_e32 v75, 0xffff0000, v171
	v_and_b32_e32 v74, 0xffff0000, v170
	v_mov_b32_e32 v69, v70
	v_mov_b32_e32 v82, v65
	v_mov_b32_e32 v83, v67
	v_mov_b32_e32 v65, v66
	v_lshlrev_b32_e32 v77, 16, v171
	v_lshlrev_b32_e32 v76, 16, v170
	v_and_b32_e32 v71, 0xffff0000, v169
	v_and_b32_e32 v70, 0xffff0000, v168
	v_lshlrev_b32_e32 v81, 16, v169
	v_lshlrev_b32_e32 v80, 16, v168
	v_lshl_add_u64 v[66:67], s[12:13], 0, v[166:167]
	v_lshl_add_u64 v[66:67], v[66:67], 0, v[164:165]
	v_pk_add_f32 v[78:79], v[78:79], v[72:73] op_sel_hi:[1,0]
	v_pk_add_f32 v[68:69], v[68:69], v[72:73] op_sel_hi:[1,0]
	v_pk_add_f32 v[82:83], v[82:83], v[72:73] op_sel_hi:[1,0]
	v_pk_add_f32 v[64:65], v[64:65], v[72:73] op_sel_hi:[1,0]
	v_pk_mul_f32 v[72:73], v[78:79], v[74:75]
	v_pk_mul_f32 v[68:69], v[68:69], v[76:77]
	v_pk_mul_f32 v[70:71], v[82:83], v[70:71]
	v_pk_mul_f32 v[64:65], v[64:65], v[80:81]
	v_and_b32_sdwa v76, v73, v233 dst_sel:DWORD dst_unused:UNUSED_PAD src0_sel:WORD_1 src1_sel:DWORD
	v_and_b32_sdwa v77, v72, v233 dst_sel:DWORD dst_unused:UNUSED_PAD src0_sel:WORD_1 src1_sel:DWORD
	v_and_b32_sdwa v74, v69, v233 dst_sel:DWORD dst_unused:UNUSED_PAD src0_sel:WORD_1 src1_sel:DWORD
	v_and_b32_sdwa v75, v68, v233 dst_sel:DWORD dst_unused:UNUSED_PAD src0_sel:WORD_1 src1_sel:DWORD
	v_and_b32_sdwa v78, v65, v233 dst_sel:DWORD dst_unused:UNUSED_PAD src0_sel:WORD_1 src1_sel:DWORD
	v_and_b32_sdwa v79, v64, v233 dst_sel:DWORD dst_unused:UNUSED_PAD src0_sel:WORD_1 src1_sel:DWORD
	v_and_b32_sdwa v80, v71, v233 dst_sel:DWORD dst_unused:UNUSED_PAD src0_sel:WORD_1 src1_sel:DWORD
	v_and_b32_sdwa v81, v70, v233 dst_sel:DWORD dst_unused:UNUSED_PAD src0_sel:WORD_1 src1_sel:DWORD
	v_add3_u32 v73, v73, v76, s37
	v_add3_u32 v72, v72, v77, s37
	v_add3_u32 v68, v68, v75, s37
	v_add3_u32 v69, v69, v74, s37
	v_add3_u32 v74, v64, v79, s37
	v_add3_u32 v75, v65, v78, s37
	v_add3_u32 v64, v71, v80, s37
	v_add3_u32 v65, v70, v81, s37
	v_and_b32_e32 v70, 0xffff0000, v73
	v_and_b32_e32 v71, 0xffff0000, v72
	v_and_b32_e32 v72, 0xffff0000, v64
	v_and_b32_e32 v73, 0xffff0000, v65
	v_or_b32_sdwa v65, v70, v69 dst_sel:DWORD dst_unused:UNUSED_PAD src0_sel:DWORD src1_sel:WORD_1
	v_or_b32_sdwa v64, v71, v68 dst_sel:DWORD dst_unused:UNUSED_PAD src0_sel:DWORD src1_sel:WORD_1
	v_or_b32_sdwa v69, v72, v75 dst_sel:DWORD dst_unused:UNUSED_PAD src0_sel:DWORD src1_sel:WORD_1
	v_or_b32_sdwa v68, v73, v74 dst_sel:DWORD dst_unused:UNUSED_PAD src0_sel:DWORD src1_sel:WORD_1
	global_store_dwordx2 v[66:67], v[64:65], off
	global_store_dwordx2 v[66:67], v[68:69], off offset:32
	s_branch .LBB0_716

; __device__ __forceinline__ unsigned xb_ld(unsigned* p)              { return __hip_atomic_load(p, __ATOMIC_RELAXED, __HIP_MEMORY_SCOPE_AGENT); }
; #define XB_SPIN(cond, bar) do { unsigned _sp = 0; while (cond) { __builtin_amdgcn_s_sleep(1); \
;     if ((++_sp & 255u) == 0u) { if (xb_ld(&(bar)[XB_TMO])) break; if (_sp > XB_SPIN_CAP) { atomicAdd(&(bar)[XB_TMO], 1u); break; } } } } while (0)
; __device__ __forceinline__ void xcd_barrier(const XcdBarrier& b, const bool local_only = false) {
;     ...
;         } else {
;             XB_SPIN(xb_ld(&bar[XB_XGEN(b.x)]) == gen, bar);
;             __builtin_amdgcn_fence(__ATOMIC_ACQUIRE, "agent");
;             asm volatile("s_waitcnt vmcnt(0)" ::: "memory");
;         }
.LBB0_757:
	s_or_b64 exec, exec, s[12:13]
.Lxb_arr_5:
	s_waitcnt vmcnt(0) lgkmcnt(0)
	v_readlane_b32 vcc_lo, v253, 2
	v_readlane_b32 vcc_hi, v253, 3
	s_nop 0
	s_and_b64 vcc, exec, vcc
	s_cbranch_vccz .Lxb_nl_skip_9
	buffer_inv sc1
.Lxb_nl_skip_9:
	s_waitcnt vmcnt(0)

; __device__ __forceinline__ unsigned xb_ld(unsigned* p)              { return __hip_atomic_load(p, __ATOMIC_RELAXED, __HIP_MEMORY_SCOPE_AGENT); }
; #define XB_SPIN(cond, bar) do { unsigned _sp = 0; while (cond) { __builtin_amdgcn_s_sleep(1); \
;     if ((++_sp & 255u) == 0u) { if (xb_ld(&(bar)[XB_TMO])) break; if (_sp > XB_SPIN_CAP) { atomicAdd(&(bar)[XB_TMO], 1u); break; } } } } while (0)
; __device__ __forceinline__ void xcd_barrier(const XcdBarrier& b, const bool local_only = false) {
;     ...
;         } else {
;             XB_SPIN(xb_ld(&bar[XB_XGEN(b.x)]) == gen, bar);
;             __builtin_amdgcn_fence(__ATOMIC_ACQUIRE, "agent");
;             asm volatile("s_waitcnt vmcnt(0)" ::: "memory");
.Lxb_gen_6:
	v_mov_b32_e32 v0, 0x2000
	global_load_dword v0, v0, s[4:5] offset:1024 sc1
	s_add_u32 s18, s4, 0x2400
	s_addc_u32 s19, s5, 0
	s_waitcnt vmcnt(0)
	v_cmp_eq_u32_e32 vcc, v0, v1
	s_and_saveexec_b64 s[12:13], vcc
	s_cbranch_execz .LBB0_898
	s_add_u32 s14, s0, 0x1200
	s_addc_u32 s15, s1, 0
	s_mov_b32 s38, 1
	s_mov_b64 s[20:21], 0
	s_branch .LBB0_889

; __device__ __forceinline__ unsigned xb_ld(unsigned* p)              { return __hip_atomic_load(p, __ATOMIC_RELAXED, __HIP_MEMORY_SCOPE_AGENT); }
; #define XB_SPIN(cond, bar) do { unsigned _sp = 0; while (cond) { __builtin_amdgcn_s_sleep(1); \
;     if ((++_sp & 255u) == 0u) { if (xb_ld(&(bar)[XB_TMO])) break; if (_sp > XB_SPIN_CAP) { atomicAdd(&(bar)[XB_TMO], 1u); break; } } } } while (0)
; __device__ __forceinline__ void xcd_barrier(const XcdBarrier& b, const bool local_only = false) {
;     ...
;         } else {
;             XB_SPIN(xb_ld(&bar[XB_XGEN(b.x)]) == gen, bar);
;             __builtin_amdgcn_fence(__ATOMIC_ACQUIRE, "agent");
;             asm volatile("s_waitcnt vmcnt(0)" ::: "memory");
;         }
.LBB0_898:
	s_or_b64 exec, exec, s[12:13]
.Lxb_arr_6:
	s_waitcnt vmcnt(0) lgkmcnt(0)
	v_readlane_b32 vcc_lo, v253, 2
	v_readlane_b32 vcc_hi, v253, 3
	s_nop 0
	s_and_b64 vcc, exec, vcc
	s_cbranch_vccz .Lxb_nl_skip_11
	buffer_inv sc1
.Lxb_nl_skip_11:
	s_waitcnt vmcnt(0)

; __device__ __forceinline__ unsigned xb_ld(unsigned* p)              { return __hip_atomic_load(p, __ATOMIC_RELAXED, __HIP_MEMORY_SCOPE_AGENT); }
; #define XB_SPIN(cond, bar) do { unsigned _sp = 0; while (cond) { __builtin_amdgcn_s_sleep(1); \
;     if ((++_sp & 255u) == 0u) { if (xb_ld(&(bar)[XB_TMO])) break; if (_sp > XB_SPIN_CAP) { atomicAdd(&(bar)[XB_TMO], 1u); break; } } } } while (0)
; __device__ __forceinline__ void xcd_barrier(const XcdBarrier& b, const bool local_only = false) {
;     ...
;         } else {
;             XB_SPIN(xb_ld(&bar[XB_XGEN(b.x)]) == gen, bar);
;             __builtin_amdgcn_fence(__ATOMIC_ACQUIRE, "agent");
;             asm volatile("s_waitcnt vmcnt(0)" ::: "memory");
;         }
.LBB0_933:
	s_or_b64 exec, exec, s[12:13]
.Lxb_arr_7:
	s_waitcnt vmcnt(0) lgkmcnt(0)
	v_readlane_b32 vcc_lo, v253, 2
	v_readlane_b32 vcc_hi, v253, 3
	s_nop 0
	s_and_b64 vcc, exec, vcc
	s_cbranch_vccz .Lxb_nl_skip_12
	buffer_inv sc1
.Lxb_nl_skip_12:
	s_waitcnt vmcnt(0)

; __device__ __forceinline__ unsigned xb_ld(unsigned* p)              { return __hip_atomic_load(p, __ATOMIC_RELAXED, __HIP_MEMORY_SCOPE_AGENT); }
; #define XB_SPIN(cond, bar) do { unsigned _sp = 0; while (cond) { __builtin_amdgcn_s_sleep(1); \
;     if ((++_sp & 255u) == 0u) { if (xb_ld(&(bar)[XB_TMO])) break; if (_sp > XB_SPIN_CAP) { atomicAdd(&(bar)[XB_TMO], 1u); break; } } } } while (0)
; __device__ __forceinline__ void xcd_barrier(const XcdBarrier& b, const bool local_only = false) {
;     ...
;         } else {
;             XB_SPIN(xb_ld(&bar[XB_XGEN(b.x)]) == gen, bar);
;             __builtin_amdgcn_fence(__ATOMIC_ACQUIRE, "agent");
;             asm volatile("s_waitcnt vmcnt(0)" ::: "memory");
;         }
.LBB0_1097:
	s_or_b64 exec, exec, s[12:13]
.Lxb_arr_8:
	s_waitcnt vmcnt(0) lgkmcnt(0)
	v_readlane_b32 vcc_lo, v253, 2
	v_readlane_b32 vcc_hi, v253, 3
	s_nop 0
	s_and_b64 vcc, exec, vcc
	s_cbranch_vccz .Lxb_nl_skip_14
	buffer_inv sc1
.Lxb_nl_skip_14:
	s_waitcnt vmcnt(0)
